# scan: consumer+producer loops fully 8-byte aligned (e64 encodings + s_nop pads), one lgkm wait per 2 steps, prefetch 3 steps, deferred transposes
# baseline (speedup 1.0000x reference)
.Lscan_cons_chunk:
	s_nop 0
	v_cndmask_b32_e64 v2, v4, v5, s[42:43]
	v_add_lshl_u32 v2, v2, s80, 10
	v_mov_b32_e64 v3, v180
	s_add_i32 s28, s28, 0x10000
	v_lshl_add_u64 v[2:3], v[0:1], 0, v[2:3]
	v_add_u32_e64 v5, 64, v5
	v_subrev_u32_e64 v4, 64, v4
	s_waitcnt lgkmcnt(3)
	s_nop 0
	v_fma_mix_f32 v12, v6, v20, v180 op_sel_hi:[0,1,0]
	v_fma_mix_f32 v12, v7, v20, v12 op_sel:[0,1,0] op_sel_hi:[0,1,0]
	v_fma_mix_f32 v12, v8, v21, v12 op_sel_hi:[0,1,0]
	v_fma_mix_f32 v12, v9, v21, v12 op_sel:[0,1,0] op_sel_hi:[0,1,0]
	s_nop 1
	s_nop 0
	v_add_f32_dpp v12, v12, v12 row_ror:1 row_mask:0xf bank_mask:0xf bound_ctrl:1
	s_nop 1
	s_nop 0
	v_add_f32_dpp v12, v12, v12 row_ror:2 row_mask:0xf bank_mask:0xf bound_ctrl:1
	v_pk_fma_f32 v[48:49], v[28:29], v[66:67], v[6:7] op_sel_hi:[1,0,1]
	v_pk_fma_f32 v[50:51], v[30:31], v[66:67], v[8:9] op_sel_hi:[1,0,1]
	v_add_f32_dpp v12, v12, v12 row_ror:4 row_mask:0xf bank_mask:0xf bound_ctrl:1
	v_add_f32_dpp v130, v130, v130 row_ror:8 row_mask:0xf bank_mask:0xc
	v_add_f32_dpp v130, v122, v122 row_ror:8 row_mask:0xf bank_mask:0x3
	v_add_f32_dpp v131, v131, v131 row_ror:8 row_mask:0xf bank_mask:0xc
	v_add_f32_dpp v12, v12, v12 row_ror:8 row_mask:0xf bank_mask:0xf bound_ctrl:1
	v_pk_fma_f32 v[6:7], v[24:25], v[12:13], v[48:49] op_sel_hi:[1,0,1] neg_lo:[1,0,0] neg_hi:[1,0,0]
	v_pk_fma_f32 v[8:9], v[26:27], v[12:13], v[50:51] op_sel_hi:[1,0,1] neg_lo:[1,0,0] neg_hi:[1,0,0]
	ds_read_b128 v[110:113], v10 offset:3328
	ds_read_b128 v[106:109], v10 offset:3072
	ds_read_b128 v[118:121], v10 offset:3840
	ds_read_b128 v[114:117], v10 offset:3584
	v_fma_mix_f32 v12, v6, v36, v180 op_sel_hi:[0,1,0]
	v_fma_mix_f32 v12, v7, v36, v12 op_sel:[0,1,0] op_sel_hi:[0,1,0]
	v_fma_mix_f32 v12, v8, v37, v12 op_sel_hi:[0,1,0]
	v_fma_mix_f32 v12, v9, v37, v12 op_sel:[0,1,0] op_sel_hi:[0,1,0]
	v_fma_mix_f32 v52, v6, v22, v180 op_sel_hi:[0,1,0]
	v_fma_mix_f32 v52, v7, v22, v52 op_sel:[0,1,0] op_sel_hi:[0,1,0]
	v_add_f32_dpp v12, v12, v12 row_ror:1 row_mask:0xf bank_mask:0xf bound_ctrl:1
	v_fma_mix_f32 v52, v8, v23, v52 op_sel_hi:[0,1,0]
	v_fma_mix_f32 v52, v9, v23, v52 op_sel:[0,1,0] op_sel_hi:[0,1,0]
	v_add_f32_dpp v12, v12, v12 row_ror:2 row_mask:0xf bank_mask:0xf bound_ctrl:1
	v_pk_fma_f32 v[48:49], v[44:45], v[66:67], v[6:7] op_sel:[0,1,0]
	v_pk_fma_f32 v[50:51], v[46:47], v[66:67], v[8:9] op_sel:[0,1,0]
	v_add_f32_dpp v12, v12, v12 row_ror:4 row_mask:0xf bank_mask:0xf bound_ctrl:1
	v_add_f32_dpp v131, v123, v123 row_ror:8 row_mask:0xf bank_mask:0x3
	v_add_f32_dpp v132, v132, v132 row_ror:8 row_mask:0xf bank_mask:0xc
	v_add_f32_dpp v132, v124, v124 row_ror:8 row_mask:0xf bank_mask:0x3
	v_add_f32_dpp v12, v12, v12 row_ror:8 row_mask:0xf bank_mask:0xf bound_ctrl:1
	v_pk_fma_f32 v[6:7], v[40:41], v[12:13], v[48:49] op_sel_hi:[1,0,1] neg_lo:[1,0,0] neg_hi:[1,0,0]
	v_pk_fma_f32 v[8:9], v[42:43], v[12:13], v[50:51] op_sel_hi:[1,0,1] neg_lo:[1,0,0] neg_hi:[1,0,0]
	ds_read_b128 v[142:145], v10 offset:4352
	ds_read_b128 v[150:153], v10 offset:4864
	ds_read_b128 v[146:149], v10 offset:4608
	ds_read_b128 v[70:73], v11 offset:256
	s_waitcnt lgkmcnt(4)
	s_nop 0
	v_fma_mix_f32 v12, v6, v88, v180 op_sel_hi:[0,1,0]
	v_fma_mix_f32 v12, v7, v88, v12 op_sel:[0,1,0] op_sel_hi:[0,1,0]
	v_fma_mix_f32 v12, v8, v89, v12 op_sel_hi:[0,1,0]
	v_fma_mix_f32 v12, v9, v89, v12 op_sel:[0,1,0] op_sel_hi:[0,1,0]
	v_fma_mix_f32 v53, v6, v38, v180 op_sel_hi:[0,1,0]
	v_fma_mix_f32 v53, v7, v38, v53 op_sel:[0,1,0] op_sel_hi:[0,1,0]
	v_add_f32_dpp v12, v12, v12 row_ror:1 row_mask:0xf bank_mask:0xf bound_ctrl:1
	v_fma_mix_f32 v53, v8, v39, v53 op_sel_hi:[0,1,0]
	v_fma_mix_f32 v53, v9, v39, v53 op_sel:[0,1,0] op_sel_hi:[0,1,0]
	v_add_f32_dpp v12, v12, v12 row_ror:2 row_mask:0xf bank_mask:0xf bound_ctrl:1
	v_pk_fma_f32 v[48:49], v[96:97], v[68:69], v[6:7] op_sel_hi:[1,0,1]
	v_pk_fma_f32 v[50:51], v[98:99], v[68:69], v[8:9] op_sel_hi:[1,0,1]
	v_add_f32_dpp v12, v12, v12 row_ror:4 row_mask:0xf bank_mask:0xf bound_ctrl:1
	v_add_f32_dpp v133, v133, v133 row_ror:8 row_mask:0xf bank_mask:0xc
	v_add_f32_dpp v133, v125, v125 row_ror:8 row_mask:0xf bank_mask:0x3
	v_add_f32_dpp v134, v134, v134 row_ror:8 row_mask:0xf bank_mask:0xc
	v_add_f32_dpp v12, v12, v12 row_ror:8 row_mask:0xf bank_mask:0xf bound_ctrl:1
	v_pk_fma_f32 v[6:7], v[92:93], v[12:13], v[48:49] op_sel_hi:[1,0,1] neg_lo:[1,0,0] neg_hi:[1,0,0]
	v_pk_fma_f32 v[8:9], v[94:95], v[12:13], v[50:51] op_sel_hi:[1,0,1] neg_lo:[1,0,0] neg_hi:[1,0,0]
	ds_read_b128 v[158:161], v10 offset:5376
	ds_read_b128 v[166:169], v10 offset:5888
	ds_read_b128 v[162:165], v10 offset:5632
	v_fma_mix_f32 v12, v6, v110, v180 op_sel_hi:[0,1,0]
	v_fma_mix_f32 v12, v7, v110, v12 op_sel:[0,1,0] op_sel_hi:[0,1,0]
	v_fma_mix_f32 v12, v8, v111, v12 op_sel_hi:[0,1,0]
	v_fma_mix_f32 v12, v9, v111, v12 op_sel:[0,1,0] op_sel_hi:[0,1,0]
	v_fma_mix_f32 v54, v6, v90, v180 op_sel_hi:[0,1,0]
	v_fma_mix_f32 v54, v7, v90, v54 op_sel:[0,1,0] op_sel_hi:[0,1,0]
	v_add_f32_dpp v12, v12, v12 row_ror:1 row_mask:0xf bank_mask:0xf bound_ctrl:1
	v_fma_mix_f32 v54, v8, v91, v54 op_sel_hi:[0,1,0]
	v_fma_mix_f32 v54, v9, v91, v54 op_sel:[0,1,0] op_sel_hi:[0,1,0]
	v_add_f32_dpp v12, v12, v12 row_ror:2 row_mask:0xf bank_mask:0xf bound_ctrl:1
	v_pk_fma_f32 v[48:49], v[118:119], v[68:69], v[6:7] op_sel:[0,1,0]
	v_pk_fma_f32 v[50:51], v[120:121], v[68:69], v[8:9] op_sel:[0,1,0]
	v_add_f32_dpp v12, v12, v12 row_ror:4 row_mask:0xf bank_mask:0xf bound_ctrl:1
	v_add_f32_dpp v134, v126, v126 row_ror:8 row_mask:0xf bank_mask:0x3
	v_add_f32_dpp v135, v135, v135 row_ror:8 row_mask:0xf bank_mask:0xc
	v_add_f32_dpp v135, v127, v127 row_ror:8 row_mask:0xf bank_mask:0x3
	v_add_f32_dpp v12, v12, v12 row_ror:8 row_mask:0xf bank_mask:0xf bound_ctrl:1
	v_pk_fma_f32 v[6:7], v[114:115], v[12:13], v[48:49] op_sel_hi:[1,0,1] neg_lo:[1,0,0] neg_hi:[1,0,0]
	v_pk_fma_f32 v[8:9], v[116:117], v[12:13], v[50:51] op_sel_hi:[1,0,1] neg_lo:[1,0,0] neg_hi:[1,0,0]
	v_pk_mul_f32 v[6:7], v[6:7], v[106:107]
	v_pk_mul_f32 v[8:9], v[8:9], v[108:109]
	ds_read_b128 v[188:191], v10 offset:6400
	ds_read_b128 v[196:199], v10 offset:6912
	ds_read_b128 v[192:195], v10 offset:6656
	s_waitcnt lgkmcnt(3)
	s_nop 0
	v_fma_mix_f32 v12, v6, v142, v180 op_sel_hi:[0,1,0]
	v_fma_mix_f32 v12, v7, v142, v12 op_sel:[0,1,0] op_sel_hi:[0,1,0]
	v_fma_mix_f32 v12, v8, v143, v12 op_sel_hi:[0,1,0]
	v_fma_mix_f32 v12, v9, v143, v12 op_sel:[0,1,0] op_sel_hi:[0,1,0]
	v_fma_mix_f32 v55, v6, v112, v180 op_sel_hi:[0,1,0]
	v_fma_mix_f32 v55, v7, v112, v55 op_sel:[0,1,0] op_sel_hi:[0,1,0]
	v_add_f32_dpp v12, v12, v12 row_ror:1 row_mask:0xf bank_mask:0xf bound_ctrl:1
	v_fma_mix_f32 v55, v8, v113, v55 op_sel_hi:[0,1,0]
	v_fma_mix_f32 v55, v9, v113, v55 op_sel:[0,1,0] op_sel_hi:[0,1,0]
	v_add_f32_dpp v12, v12, v12 row_ror:2 row_mask:0xf bank_mask:0xf bound_ctrl:1
	v_pk_fma_f32 v[48:49], v[150:151], v[70:71], v[6:7] op_sel_hi:[1,0,1]
	v_pk_fma_f32 v[50:51], v[152:153], v[70:71], v[8:9] op_sel_hi:[1,0,1]
	v_add_f32_dpp v12, v12, v12 row_ror:4 row_mask:0xf bank_mask:0xf bound_ctrl:1
	v_add_f32_dpp v136, v136, v136 row_ror:8 row_mask:0xf bank_mask:0xc
	v_add_f32_dpp v136, v128, v128 row_ror:8 row_mask:0xf bank_mask:0x3
	v_add_f32_dpp v12, v12, v12 row_ror:8 row_mask:0xf bank_mask:0xf bound_ctrl:1
	v_pk_fma_f32 v[6:7], v[146:147], v[12:13], v[48:49] op_sel_hi:[1,0,1] neg_lo:[1,0,0] neg_hi:[1,0,0]
	v_pk_fma_f32 v[8:9], v[148:149], v[12:13], v[50:51] op_sel_hi:[1,0,1] neg_lo:[1,0,0] neg_hi:[1,0,0]
	ds_read_b128 v[204:207], v10 offset:7424
	ds_read_b128 v[200:203], v10 offset:7168
	ds_read_b128 v[212:215], v10 offset:7936
	ds_read_b128 v[208:211], v10 offset:7680
	v_fma_mix_f32 v12, v6, v158, v180 op_sel_hi:[0,1,0]
	v_fma_mix_f32 v12, v7, v158, v12 op_sel:[0,1,0] op_sel_hi:[0,1,0]
	v_fma_mix_f32 v12, v8, v159, v12 op_sel_hi:[0,1,0]
	v_fma_mix_f32 v12, v9, v159, v12 op_sel:[0,1,0] op_sel_hi:[0,1,0]
	v_fma_mix_f32 v56, v6, v144, v180 op_sel_hi:[0,1,0]
	v_fma_mix_f32 v56, v7, v144, v56 op_sel:[0,1,0] op_sel_hi:[0,1,0]
	v_add_f32_dpp v12, v12, v12 row_ror:1 row_mask:0xf bank_mask:0xf bound_ctrl:1
	v_fma_mix_f32 v56, v8, v145, v56 op_sel_hi:[0,1,0]
	v_fma_mix_f32 v56, v9, v145, v56 op_sel:[0,1,0] op_sel_hi:[0,1,0]
	v_add_f32_dpp v12, v12, v12 row_ror:2 row_mask:0xf bank_mask:0xf bound_ctrl:1
	v_pk_fma_f32 v[48:49], v[166:167], v[70:71], v[6:7] op_sel:[0,1,0]
	v_pk_fma_f32 v[50:51], v[168:169], v[70:71], v[8:9] op_sel:[0,1,0]
	v_add_f32_dpp v12, v12, v12 row_ror:4 row_mask:0xf bank_mask:0xf bound_ctrl:1
	v_add_f32_dpp v137, v137, v137 row_ror:8 row_mask:0xf bank_mask:0xc
	v_add_f32_dpp v137, v129, v129 row_ror:8 row_mask:0xf bank_mask:0x3
	v_add_f32_dpp v12, v12, v12 row_ror:8 row_mask:0xf bank_mask:0xf bound_ctrl:1
	v_pk_fma_f32 v[6:7], v[162:163], v[12:13], v[48:49] op_sel_hi:[1,0,1] neg_lo:[1,0,0] neg_hi:[1,0,0]
	v_pk_fma_f32 v[8:9], v[164:165], v[12:13], v[50:51] op_sel_hi:[1,0,1] neg_lo:[1,0,0] neg_hi:[1,0,0]
	ds_read_b128 v[20:23], v10 offset:8448
	ds_read_b128 v[28:31], v10 offset:8960
	ds_read_b128 v[24:27], v10 offset:8704
	ds_read_b128 v[66:69], v11 offset:512
	s_waitcnt lgkmcnt(4)
	s_nop 0
	v_fma_mix_f32 v12, v6, v188, v180 op_sel_hi:[0,1,0]
	v_fma_mix_f32 v12, v7, v188, v12 op_sel:[0,1,0] op_sel_hi:[0,1,0]
	v_fma_mix_f32 v12, v8, v189, v12 op_sel_hi:[0,1,0]
	v_fma_mix_f32 v12, v9, v189, v12 op_sel:[0,1,0] op_sel_hi:[0,1,0]
	v_fma_mix_f32 v57, v6, v160, v180 op_sel_hi:[0,1,0]
	v_fma_mix_f32 v57, v7, v160, v57 op_sel:[0,1,0] op_sel_hi:[0,1,0]
	v_add_f32_dpp v12, v12, v12 row_ror:1 row_mask:0xf bank_mask:0xf bound_ctrl:1
	v_fma_mix_f32 v57, v8, v161, v57 op_sel_hi:[0,1,0]
	v_fma_mix_f32 v57, v9, v161, v57 op_sel:[0,1,0] op_sel_hi:[0,1,0]
	v_add_f32_dpp v12, v12, v12 row_ror:2 row_mask:0xf bank_mask:0xf bound_ctrl:1
	v_pk_fma_f32 v[48:49], v[196:197], v[72:73], v[6:7] op_sel_hi:[1,0,1]
	v_pk_fma_f32 v[50:51], v[198:199], v[72:73], v[8:9] op_sel_hi:[1,0,1]
	v_add_f32_dpp v12, v12, v12 row_ror:4 row_mask:0xf bank_mask:0xf bound_ctrl:1
	v_add_f32_dpp v134, v134, v134 row_ror:4 row_mask:0xf bank_mask:0xa
	v_add_f32_dpp v134, v130, v130 row_ror:12 row_mask:0xf bank_mask:0x5
	v_add_f32_dpp v135, v135, v135 row_ror:4 row_mask:0xf bank_mask:0xa
	v_add_f32_dpp v12, v12, v12 row_ror:8 row_mask:0xf bank_mask:0xf bound_ctrl:1
	v_pk_fma_f32 v[6:7], v[192:193], v[12:13], v[48:49] op_sel_hi:[1,0,1] neg_lo:[1,0,0] neg_hi:[1,0,0]
	v_pk_fma_f32 v[8:9], v[194:195], v[12:13], v[50:51] op_sel_hi:[1,0,1] neg_lo:[1,0,0] neg_hi:[1,0,0]
	ds_read_b128 v[36:39], v10 offset:9472
	ds_read_b128 v[44:47], v10 offset:9984
	ds_read_b128 v[40:43], v10 offset:9728
	v_fma_mix_f32 v12, v6, v204, v180 op_sel_hi:[0,1,0]
	v_fma_mix_f32 v12, v7, v204, v12 op_sel:[0,1,0] op_sel_hi:[0,1,0]
	v_fma_mix_f32 v12, v8, v205, v12 op_sel_hi:[0,1,0]
	v_fma_mix_f32 v12, v9, v205, v12 op_sel:[0,1,0] op_sel_hi:[0,1,0]
	v_fma_mix_f32 v81, v6, v190, v180 op_sel_hi:[0,1,0]
	v_fma_mix_f32 v81, v7, v190, v81 op_sel:[0,1,0] op_sel_hi:[0,1,0]
	v_add_f32_dpp v12, v12, v12 row_ror:1 row_mask:0xf bank_mask:0xf bound_ctrl:1
	v_fma_mix_f32 v81, v8, v191, v81 op_sel_hi:[0,1,0]
	v_fma_mix_f32 v81, v9, v191, v81 op_sel:[0,1,0] op_sel_hi:[0,1,0]
	v_add_f32_dpp v12, v12, v12 row_ror:2 row_mask:0xf bank_mask:0xf bound_ctrl:1
	v_pk_fma_f32 v[48:49], v[212:213], v[72:73], v[6:7] op_sel:[0,1,0]
	v_pk_fma_f32 v[50:51], v[214:215], v[72:73], v[8:9] op_sel:[0,1,0]
	v_add_f32_dpp v12, v12, v12 row_ror:4 row_mask:0xf bank_mask:0xf bound_ctrl:1
	v_add_f32_dpp v135, v131, v131 row_ror:12 row_mask:0xf bank_mask:0x5
	v_add_f32_dpp v136, v136, v136 row_ror:4 row_mask:0xf bank_mask:0xa
	v_add_f32_dpp v136, v132, v132 row_ror:12 row_mask:0xf bank_mask:0x5
	v_add_f32_dpp v12, v12, v12 row_ror:8 row_mask:0xf bank_mask:0xf bound_ctrl:1
	v_pk_fma_f32 v[6:7], v[208:209], v[12:13], v[48:49] op_sel_hi:[1,0,1] neg_lo:[1,0,0] neg_hi:[1,0,0]
	v_pk_fma_f32 v[8:9], v[210:211], v[12:13], v[50:51] op_sel_hi:[1,0,1] neg_lo:[1,0,0] neg_hi:[1,0,0]
	v_pk_mul_f32 v[6:7], v[6:7], v[200:201]
	v_pk_mul_f32 v[8:9], v[8:9], v[202:203]
	ds_read_b128 v[88:91], v10 offset:10496
	ds_read_b128 v[96:99], v10 offset:11008
	ds_read_b128 v[92:95], v10 offset:10752
	s_waitcnt lgkmcnt(3)
	s_nop 0
	v_fma_mix_f32 v12, v6, v20, v180 op_sel_hi:[0,1,0]
	v_fma_mix_f32 v12, v7, v20, v12 op_sel:[0,1,0] op_sel_hi:[0,1,0]
	v_fma_mix_f32 v12, v8, v21, v12 op_sel_hi:[0,1,0]
	v_fma_mix_f32 v12, v9, v21, v12 op_sel:[0,1,0] op_sel_hi:[0,1,0]
	v_fma_mix_f32 v82, v6, v206, v180 op_sel_hi:[0,1,0]
	v_fma_mix_f32 v82, v7, v206, v82 op_sel:[0,1,0] op_sel_hi:[0,1,0]
	v_add_f32_dpp v12, v12, v12 row_ror:1 row_mask:0xf bank_mask:0xf bound_ctrl:1
	v_fma_mix_f32 v82, v8, v207, v82 op_sel_hi:[0,1,0]
	v_fma_mix_f32 v82, v9, v207, v82 op_sel:[0,1,0] op_sel_hi:[0,1,0]
	v_add_f32_dpp v12, v12, v12 row_ror:2 row_mask:0xf bank_mask:0xf bound_ctrl:1
	v_pk_fma_f32 v[48:49], v[28:29], v[66:67], v[6:7] op_sel_hi:[1,0,1]
	v_pk_fma_f32 v[50:51], v[30:31], v[66:67], v[8:9] op_sel_hi:[1,0,1]
	v_add_f32_dpp v12, v12, v12 row_ror:4 row_mask:0xf bank_mask:0xf bound_ctrl:1
	v_add_f32_dpp v137, v137, v137 row_ror:4 row_mask:0xf bank_mask:0xa
	v_add_f32_dpp v137, v133, v133 row_ror:12 row_mask:0xf bank_mask:0x5
	v_add_f32_dpp v12, v12, v12 row_ror:8 row_mask:0xf bank_mask:0xf bound_ctrl:1
	v_pk_fma_f32 v[6:7], v[24:25], v[12:13], v[48:49] op_sel_hi:[1,0,1] neg_lo:[1,0,0] neg_hi:[1,0,0]
	v_pk_fma_f32 v[8:9], v[26:27], v[12:13], v[50:51] op_sel_hi:[1,0,1] neg_lo:[1,0,0] neg_hi:[1,0,0]
	ds_read_b128 v[110:113], v10 offset:11520
	ds_read_b128 v[106:109], v10 offset:11264
	ds_read_b128 v[118:121], v10 offset:12032
	ds_read_b128 v[114:117], v10 offset:11776
	v_fma_mix_f32 v12, v6, v36, v180 op_sel_hi:[0,1,0]
	v_fma_mix_f32 v12, v7, v36, v12 op_sel:[0,1,0] op_sel_hi:[0,1,0]
	v_fma_mix_f32 v12, v8, v37, v12 op_sel_hi:[0,1,0]
	v_fma_mix_f32 v12, v9, v37, v12 op_sel:[0,1,0] op_sel_hi:[0,1,0]
	v_fma_mix_f32 v83, v6, v22, v180 op_sel_hi:[0,1,0]
	v_fma_mix_f32 v83, v7, v22, v83 op_sel:[0,1,0] op_sel_hi:[0,1,0]
	v_add_f32_dpp v12, v12, v12 row_ror:1 row_mask:0xf bank_mask:0xf bound_ctrl:1
	v_fma_mix_f32 v83, v8, v23, v83 op_sel_hi:[0,1,0]
	v_fma_mix_f32 v83, v9, v23, v83 op_sel:[0,1,0] op_sel_hi:[0,1,0]
	v_add_f32_dpp v12, v12, v12 row_ror:2 row_mask:0xf bank_mask:0xf bound_ctrl:1
	v_pk_fma_f32 v[48:49], v[44:45], v[66:67], v[6:7] op_sel:[0,1,0]
	v_pk_fma_f32 v[50:51], v[46:47], v[66:67], v[8:9] op_sel:[0,1,0]
	v_add_f32_dpp v12, v12, v12 row_ror:4 row_mask:0xf bank_mask:0xf bound_ctrl:1
	v_cndmask_b32_e64 v62, v136, v134, s[38:39]
	v_cndmask_b32_e64 v63, v134, v136, s[38:39]
	v_add_f32_dpp v12, v12, v12 row_ror:8 row_mask:0xf bank_mask:0xf bound_ctrl:1
	v_pk_fma_f32 v[6:7], v[40:41], v[12:13], v[48:49] op_sel_hi:[1,0,1] neg_lo:[1,0,0] neg_hi:[1,0,0]
	v_pk_fma_f32 v[8:9], v[42:43], v[12:13], v[50:51] op_sel_hi:[1,0,1] neg_lo:[1,0,0] neg_hi:[1,0,0]
	ds_read_b128 v[142:145], v10 offset:12544
	ds_read_b128 v[150:153], v10 offset:13056
	ds_read_b128 v[146:149], v10 offset:12800
	ds_read_b128 v[70:73], v11 offset:768
	s_waitcnt lgkmcnt(4)
	s_nop 0
	v_fma_mix_f32 v12, v6, v88, v180 op_sel_hi:[0,1,0]
	v_fma_mix_f32 v12, v7, v88, v12 op_sel:[0,1,0] op_sel_hi:[0,1,0]
	v_fma_mix_f32 v12, v8, v89, v12 op_sel_hi:[0,1,0]
	v_fma_mix_f32 v12, v9, v89, v12 op_sel:[0,1,0] op_sel_hi:[0,1,0]
	v_fma_mix_f32 v100, v6, v38, v180 op_sel_hi:[0,1,0]
	v_fma_mix_f32 v100, v7, v38, v100 op_sel:[0,1,0] op_sel_hi:[0,1,0]
	v_add_f32_dpp v12, v12, v12 row_ror:1 row_mask:0xf bank_mask:0xf bound_ctrl:1
	v_fma_mix_f32 v100, v8, v39, v100 op_sel_hi:[0,1,0]
	v_fma_mix_f32 v100, v9, v39, v100 op_sel:[0,1,0] op_sel_hi:[0,1,0]
	v_add_f32_dpp v12, v12, v12 row_ror:2 row_mask:0xf bank_mask:0xf bound_ctrl:1
	v_pk_fma_f32 v[48:49], v[96:97], v[68:69], v[6:7] op_sel_hi:[1,0,1]
	v_pk_fma_f32 v[50:51], v[98:99], v[68:69], v[8:9] op_sel_hi:[1,0,1]
	v_add_f32_dpp v12, v12, v12 row_ror:4 row_mask:0xf bank_mask:0xf bound_ctrl:1
	v_cndmask_b32_e64 v64, v137, v135, s[38:39]
	v_cndmask_b32_e64 v65, v135, v137, s[38:39]
	v_add_f32_dpp v12, v12, v12 row_ror:8 row_mask:0xf bank_mask:0xf bound_ctrl:1
	v_pk_fma_f32 v[6:7], v[92:93], v[12:13], v[48:49] op_sel_hi:[1,0,1] neg_lo:[1,0,0] neg_hi:[1,0,0]
	v_pk_fma_f32 v[8:9], v[94:95], v[12:13], v[50:51] op_sel_hi:[1,0,1] neg_lo:[1,0,0] neg_hi:[1,0,0]
	ds_read_b128 v[158:161], v10 offset:13568
	ds_read_b128 v[166:169], v10 offset:14080
	ds_read_b128 v[162:165], v10 offset:13824
	v_fma_mix_f32 v12, v6, v110, v180 op_sel_hi:[0,1,0]
	v_fma_mix_f32 v12, v7, v110, v12 op_sel:[0,1,0] op_sel_hi:[0,1,0]
	v_fma_mix_f32 v12, v8, v111, v12 op_sel_hi:[0,1,0]
	v_fma_mix_f32 v12, v9, v111, v12 op_sel:[0,1,0] op_sel_hi:[0,1,0]
	v_fma_mix_f32 v101, v6, v90, v180 op_sel_hi:[0,1,0]
	v_fma_mix_f32 v101, v7, v90, v101 op_sel:[0,1,0] op_sel_hi:[0,1,0]
	v_add_f32_dpp v12, v12, v12 row_ror:1 row_mask:0xf bank_mask:0xf bound_ctrl:1
	v_fma_mix_f32 v101, v8, v91, v101 op_sel_hi:[0,1,0]
	v_fma_mix_f32 v101, v9, v91, v101 op_sel:[0,1,0] op_sel_hi:[0,1,0]
	v_add_f32_dpp v12, v12, v12 row_ror:2 row_mask:0xf bank_mask:0xf bound_ctrl:1
	v_pk_fma_f32 v[48:49], v[118:119], v[68:69], v[6:7] op_sel:[0,1,0]
	v_pk_fma_f32 v[50:51], v[120:121], v[68:69], v[8:9] op_sel:[0,1,0]
	v_add_f32_dpp v12, v12, v12 row_ror:4 row_mask:0xf bank_mask:0xf bound_ctrl:1
	v_add_f32_dpp v62, v63, v62 quad_perm:[2,3,0,1] row_mask:0xf bank_mask:0xf bound_ctrl:1
	v_add_f32_dpp v63, v65, v64 quad_perm:[2,3,0,1] row_mask:0xf bank_mask:0xf bound_ctrl:1
	v_add_f32_dpp v12, v12, v12 row_ror:8 row_mask:0xf bank_mask:0xf bound_ctrl:1
	v_pk_fma_f32 v[6:7], v[114:115], v[12:13], v[48:49] op_sel_hi:[1,0,1] neg_lo:[1,0,0] neg_hi:[1,0,0]
	v_pk_fma_f32 v[8:9], v[116:117], v[12:13], v[50:51] op_sel_hi:[1,0,1] neg_lo:[1,0,0] neg_hi:[1,0,0]
	v_pk_mul_f32 v[6:7], v[6:7], v[106:107]
	v_pk_mul_f32 v[8:9], v[8:9], v[108:109]
	ds_read_b128 v[188:191], v10 offset:14592
	ds_read_b128 v[196:199], v10 offset:15104
	ds_read_b128 v[192:195], v10 offset:14848
	s_waitcnt lgkmcnt(3)
	s_nop 0
	v_fma_mix_f32 v12, v6, v142, v180 op_sel_hi:[0,1,0]
	v_fma_mix_f32 v12, v7, v142, v12 op_sel:[0,1,0] op_sel_hi:[0,1,0]
	v_fma_mix_f32 v12, v8, v143, v12 op_sel_hi:[0,1,0]
	v_fma_mix_f32 v12, v9, v143, v12 op_sel:[0,1,0] op_sel_hi:[0,1,0]
	v_fma_mix_f32 v102, v6, v112, v180 op_sel_hi:[0,1,0]
	v_fma_mix_f32 v102, v7, v112, v102 op_sel:[0,1,0] op_sel_hi:[0,1,0]
	v_add_f32_dpp v12, v12, v12 row_ror:1 row_mask:0xf bank_mask:0xf bound_ctrl:1
	v_fma_mix_f32 v102, v8, v113, v102 op_sel_hi:[0,1,0]
	v_fma_mix_f32 v102, v9, v113, v102 op_sel:[0,1,0] op_sel_hi:[0,1,0]
	v_add_f32_dpp v12, v12, v12 row_ror:2 row_mask:0xf bank_mask:0xf bound_ctrl:1
	v_pk_fma_f32 v[48:49], v[150:151], v[70:71], v[6:7] op_sel_hi:[1,0,1]
	v_pk_fma_f32 v[50:51], v[152:153], v[70:71], v[8:9] op_sel_hi:[1,0,1]
	v_add_f32_dpp v12, v12, v12 row_ror:4 row_mask:0xf bank_mask:0xf bound_ctrl:1
	v_cndmask_b32_e64 v65, v63, v62, s[40:41]
	v_cndmask_b32_e64 v62, v62, v63, s[40:41]
	v_add_f32_dpp v12, v12, v12 row_ror:8 row_mask:0xf bank_mask:0xf bound_ctrl:1
	v_pk_fma_f32 v[6:7], v[146:147], v[12:13], v[48:49] op_sel_hi:[1,0,1] neg_lo:[1,0,0] neg_hi:[1,0,0]
	v_pk_fma_f32 v[8:9], v[148:149], v[12:13], v[50:51] op_sel_hi:[1,0,1] neg_lo:[1,0,0] neg_hi:[1,0,0]
	ds_read_b128 v[204:207], v10 offset:15616
	ds_read_b128 v[200:203], v10 offset:15360
	ds_read_b128 v[212:215], v10 offset:16128
	ds_read_b128 v[208:211], v10 offset:15872
	v_fma_mix_f32 v12, v6, v158, v180 op_sel_hi:[0,1,0]
	v_fma_mix_f32 v12, v7, v158, v12 op_sel:[0,1,0] op_sel_hi:[0,1,0]
	v_fma_mix_f32 v12, v8, v159, v12 op_sel_hi:[0,1,0]
	v_fma_mix_f32 v12, v9, v159, v12 op_sel:[0,1,0] op_sel_hi:[0,1,0]
	v_fma_mix_f32 v103, v6, v144, v180 op_sel_hi:[0,1,0]
	v_fma_mix_f32 v103, v7, v144, v103 op_sel:[0,1,0] op_sel_hi:[0,1,0]
	v_add_f32_dpp v12, v12, v12 row_ror:1 row_mask:0xf bank_mask:0xf bound_ctrl:1
	v_fma_mix_f32 v103, v8, v145, v103 op_sel_hi:[0,1,0]
	v_fma_mix_f32 v103, v9, v145, v103 op_sel:[0,1,0] op_sel_hi:[0,1,0]
	v_add_f32_dpp v12, v12, v12 row_ror:2 row_mask:0xf bank_mask:0xf bound_ctrl:1
	v_pk_fma_f32 v[48:49], v[166:167], v[70:71], v[6:7] op_sel:[0,1,0]
	v_pk_fma_f32 v[50:51], v[168:169], v[70:71], v[8:9] op_sel:[0,1,0]
	v_add_f32_dpp v12, v12, v12 row_ror:4 row_mask:0xf bank_mask:0xf bound_ctrl:1
	v_add_f32_dpp v62, v62, v65 quad_perm:[1,0,3,2] row_mask:0xf bank_mask:0xf bound_ctrl:1
	v_cvt_pk_bf16_f32 v62, v62, v62
	v_add_f32_dpp v12, v12, v12 row_ror:8 row_mask:0xf bank_mask:0xf bound_ctrl:1
	v_pk_fma_f32 v[6:7], v[162:163], v[12:13], v[48:49] op_sel_hi:[1,0,1] neg_lo:[1,0,0] neg_hi:[1,0,0]
	v_pk_fma_f32 v[8:9], v[164:165], v[12:13], v[50:51] op_sel_hi:[1,0,1] neg_lo:[1,0,0] neg_hi:[1,0,0]
	ds_read_b128 v[20:23], v10 offset:16640
	ds_read_b128 v[28:31], v10 offset:17152
	ds_read_b128 v[24:27], v10 offset:16896
	ds_read_b128 v[66:69], v11 offset:1024
	s_waitcnt lgkmcnt(4)
	s_nop 0
	v_fma_mix_f32 v12, v6, v188, v180 op_sel_hi:[0,1,0]
	v_fma_mix_f32 v12, v7, v188, v12 op_sel:[0,1,0] op_sel_hi:[0,1,0]
	v_fma_mix_f32 v12, v8, v189, v12 op_sel_hi:[0,1,0]
	v_fma_mix_f32 v12, v9, v189, v12 op_sel:[0,1,0] op_sel_hi:[0,1,0]
	v_fma_mix_f32 v104, v6, v160, v180 op_sel_hi:[0,1,0]
	v_fma_mix_f32 v104, v7, v160, v104 op_sel:[0,1,0] op_sel_hi:[0,1,0]
	v_add_f32_dpp v12, v12, v12 row_ror:1 row_mask:0xf bank_mask:0xf bound_ctrl:1
	v_fma_mix_f32 v104, v8, v161, v104 op_sel_hi:[0,1,0]
	v_fma_mix_f32 v104, v9, v161, v104 op_sel:[0,1,0] op_sel_hi:[0,1,0]
	v_add_f32_dpp v12, v12, v12 row_ror:2 row_mask:0xf bank_mask:0xf bound_ctrl:1
	v_pk_fma_f32 v[48:49], v[196:197], v[72:73], v[6:7] op_sel_hi:[1,0,1]
	v_pk_fma_f32 v[50:51], v[198:199], v[72:73], v[8:9] op_sel_hi:[1,0,1]
	v_add_f32_dpp v12, v12, v12 row_ror:4 row_mask:0xf bank_mask:0xf bound_ctrl:1
	s_mov_b64 exec, s[100:101]
	s_nop 0
	global_store_short v[170:171], v62, off
	s_mov_b64 exec, -1
	s_nop 0
	v_add_f32_dpp v12, v12, v12 row_ror:8 row_mask:0xf bank_mask:0xf bound_ctrl:1
	v_pk_fma_f32 v[6:7], v[192:193], v[12:13], v[48:49] op_sel_hi:[1,0,1] neg_lo:[1,0,0] neg_hi:[1,0,0]
	v_pk_fma_f32 v[8:9], v[194:195], v[12:13], v[50:51] op_sel_hi:[1,0,1] neg_lo:[1,0,0] neg_hi:[1,0,0]
	ds_read_b128 v[36:39], v10 offset:17664
	ds_read_b128 v[44:47], v10 offset:18176
	ds_read_b128 v[40:43], v10 offset:17920
	v_fma_mix_f32 v12, v6, v204, v180 op_sel_hi:[0,1,0]
	v_fma_mix_f32 v12, v7, v204, v12 op_sel:[0,1,0] op_sel_hi:[0,1,0]
	v_fma_mix_f32 v12, v8, v205, v12 op_sel_hi:[0,1,0]
	v_fma_mix_f32 v12, v9, v205, v12 op_sel:[0,1,0] op_sel_hi:[0,1,0]
	v_fma_mix_f32 v105, v6, v190, v180 op_sel_hi:[0,1,0]
	v_fma_mix_f32 v105, v7, v190, v105 op_sel:[0,1,0] op_sel_hi:[0,1,0]
	v_add_f32_dpp v12, v12, v12 row_ror:1 row_mask:0xf bank_mask:0xf bound_ctrl:1
	v_fma_mix_f32 v105, v8, v191, v105 op_sel_hi:[0,1,0]
	v_fma_mix_f32 v105, v9, v191, v105 op_sel:[0,1,0] op_sel_hi:[0,1,0]
	v_add_f32_dpp v12, v12, v12 row_ror:2 row_mask:0xf bank_mask:0xf bound_ctrl:1
	v_pk_fma_f32 v[48:49], v[212:213], v[72:73], v[6:7] op_sel:[0,1,0]
	v_pk_fma_f32 v[50:51], v[214:215], v[72:73], v[8:9] op_sel:[0,1,0]
	v_add_f32_dpp v12, v12, v12 row_ror:4 row_mask:0xf bank_mask:0xf bound_ctrl:1
	s_nop 1
	s_nop 0
	v_add_f32_dpp v12, v12, v12 row_ror:8 row_mask:0xf bank_mask:0xf bound_ctrl:1
	v_pk_fma_f32 v[6:7], v[208:209], v[12:13], v[48:49] op_sel_hi:[1,0,1] neg_lo:[1,0,0] neg_hi:[1,0,0]
	v_pk_fma_f32 v[8:9], v[210:211], v[12:13], v[50:51] op_sel_hi:[1,0,1] neg_lo:[1,0,0] neg_hi:[1,0,0]
	v_pk_mul_f32 v[6:7], v[6:7], v[200:201]
	v_pk_mul_f32 v[8:9], v[8:9], v[202:203]
	ds_read_b128 v[88:91], v10 offset:18688
	ds_read_b128 v[96:99], v10 offset:19200
	ds_read_b128 v[92:95], v10 offset:18944
	s_waitcnt lgkmcnt(3)
	s_nop 0
	v_fma_mix_f32 v12, v6, v20, v180 op_sel_hi:[0,1,0]
	v_fma_mix_f32 v12, v7, v20, v12 op_sel:[0,1,0] op_sel_hi:[0,1,0]
	v_fma_mix_f32 v12, v8, v21, v12 op_sel_hi:[0,1,0]
	v_fma_mix_f32 v12, v9, v21, v12 op_sel:[0,1,0] op_sel_hi:[0,1,0]
	v_fma_mix_f32 v61, v6, v206, v180 op_sel_hi:[0,1,0]
	v_fma_mix_f32 v61, v7, v206, v61 op_sel:[0,1,0] op_sel_hi:[0,1,0]
	v_add_f32_dpp v12, v12, v12 row_ror:1 row_mask:0xf bank_mask:0xf bound_ctrl:1
	v_fma_mix_f32 v61, v8, v207, v61 op_sel_hi:[0,1,0]
	v_fma_mix_f32 v61, v9, v207, v61 op_sel:[0,1,0] op_sel_hi:[0,1,0]
	v_add_f32_dpp v12, v12, v12 row_ror:2 row_mask:0xf bank_mask:0xf bound_ctrl:1
	v_pk_fma_f32 v[48:49], v[28:29], v[66:67], v[6:7] op_sel_hi:[1,0,1]
	v_pk_fma_f32 v[50:51], v[30:31], v[66:67], v[8:9] op_sel_hi:[1,0,1]
	v_add_f32_dpp v12, v12, v12 row_ror:4 row_mask:0xf bank_mask:0xf bound_ctrl:1
	s_nop 1
	s_nop 0
	v_add_f32_dpp v12, v12, v12 row_ror:8 row_mask:0xf bank_mask:0xf bound_ctrl:1
	v_pk_fma_f32 v[6:7], v[24:25], v[12:13], v[48:49] op_sel_hi:[1,0,1] neg_lo:[1,0,0] neg_hi:[1,0,0]
	v_pk_fma_f32 v[8:9], v[26:27], v[12:13], v[50:51] op_sel_hi:[1,0,1] neg_lo:[1,0,0] neg_hi:[1,0,0]
	ds_read_b128 v[110:113], v10 offset:19712
	ds_read_b128 v[106:109], v10 offset:19456
	ds_read_b128 v[118:121], v10 offset:20224
	ds_read_b128 v[114:117], v10 offset:19968
	v_fma_mix_f32 v12, v6, v36, v180 op_sel_hi:[0,1,0]
	v_fma_mix_f32 v12, v7, v36, v12 op_sel:[0,1,0] op_sel_hi:[0,1,0]
	v_fma_mix_f32 v12, v8, v37, v12 op_sel_hi:[0,1,0]
	v_fma_mix_f32 v12, v9, v37, v12 op_sel:[0,1,0] op_sel_hi:[0,1,0]
	v_fma_mix_f32 v122, v6, v22, v180 op_sel_hi:[0,1,0]
	v_fma_mix_f32 v122, v7, v22, v122 op_sel:[0,1,0] op_sel_hi:[0,1,0]
	v_add_f32_dpp v12, v12, v12 row_ror:1 row_mask:0xf bank_mask:0xf bound_ctrl:1
	v_fma_mix_f32 v122, v8, v23, v122 op_sel_hi:[0,1,0]
	v_fma_mix_f32 v122, v9, v23, v122 op_sel:[0,1,0] op_sel_hi:[0,1,0]
	v_add_f32_dpp v12, v12, v12 row_ror:2 row_mask:0xf bank_mask:0xf bound_ctrl:1
	v_pk_fma_f32 v[48:49], v[44:45], v[66:67], v[6:7] op_sel:[0,1,0]
	v_pk_fma_f32 v[50:51], v[46:47], v[66:67], v[8:9] op_sel:[0,1,0]
	v_add_f32_dpp v12, v12, v12 row_ror:4 row_mask:0xf bank_mask:0xf bound_ctrl:1
	v_add_f32_dpp v83, v83, v83 row_ror:8 row_mask:0xf bank_mask:0xc
	v_add_f32_dpp v83, v52, v52 row_ror:8 row_mask:0xf bank_mask:0x3
	v_add_f32_dpp v100, v100, v100 row_ror:8 row_mask:0xf bank_mask:0xc
	v_add_f32_dpp v12, v12, v12 row_ror:8 row_mask:0xf bank_mask:0xf bound_ctrl:1
	v_pk_fma_f32 v[6:7], v[40:41], v[12:13], v[48:49] op_sel_hi:[1,0,1] neg_lo:[1,0,0] neg_hi:[1,0,0]
	v_pk_fma_f32 v[8:9], v[42:43], v[12:13], v[50:51] op_sel_hi:[1,0,1] neg_lo:[1,0,0] neg_hi:[1,0,0]
	ds_read_b128 v[142:145], v10 offset:20736
	ds_read_b128 v[150:153], v10 offset:21248
	ds_read_b128 v[146:149], v10 offset:20992
	ds_read_b128 v[70:73], v11 offset:1280
	s_waitcnt lgkmcnt(4)
	s_nop 0
	v_fma_mix_f32 v12, v6, v88, v180 op_sel_hi:[0,1,0]
	v_fma_mix_f32 v12, v7, v88, v12 op_sel:[0,1,0] op_sel_hi:[0,1,0]
	v_fma_mix_f32 v12, v8, v89, v12 op_sel_hi:[0,1,0]
	v_fma_mix_f32 v12, v9, v89, v12 op_sel:[0,1,0] op_sel_hi:[0,1,0]
	v_fma_mix_f32 v123, v6, v38, v180 op_sel_hi:[0,1,0]
	v_fma_mix_f32 v123, v7, v38, v123 op_sel:[0,1,0] op_sel_hi:[0,1,0]
	v_add_f32_dpp v12, v12, v12 row_ror:1 row_mask:0xf bank_mask:0xf bound_ctrl:1
	v_fma_mix_f32 v123, v8, v39, v123 op_sel_hi:[0,1,0]
	v_fma_mix_f32 v123, v9, v39, v123 op_sel:[0,1,0] op_sel_hi:[0,1,0]
	v_add_f32_dpp v12, v12, v12 row_ror:2 row_mask:0xf bank_mask:0xf bound_ctrl:1
	v_pk_fma_f32 v[48:49], v[96:97], v[68:69], v[6:7] op_sel_hi:[1,0,1]
	v_pk_fma_f32 v[50:51], v[98:99], v[68:69], v[8:9] op_sel_hi:[1,0,1]
	v_add_f32_dpp v12, v12, v12 row_ror:4 row_mask:0xf bank_mask:0xf bound_ctrl:1
	v_add_f32_dpp v100, v53, v53 row_ror:8 row_mask:0xf bank_mask:0x3
	v_add_f32_dpp v101, v101, v101 row_ror:8 row_mask:0xf bank_mask:0xc
	v_add_f32_dpp v101, v54, v54 row_ror:8 row_mask:0xf bank_mask:0x3
	v_add_f32_dpp v12, v12, v12 row_ror:8 row_mask:0xf bank_mask:0xf bound_ctrl:1
	v_pk_fma_f32 v[6:7], v[92:93], v[12:13], v[48:49] op_sel_hi:[1,0,1] neg_lo:[1,0,0] neg_hi:[1,0,0]
	v_pk_fma_f32 v[8:9], v[94:95], v[12:13], v[50:51] op_sel_hi:[1,0,1] neg_lo:[1,0,0] neg_hi:[1,0,0]
	ds_read_b128 v[158:161], v10 offset:21760
	ds_read_b128 v[166:169], v10 offset:22272
	ds_read_b128 v[162:165], v10 offset:22016
	v_fma_mix_f32 v12, v6, v110, v180 op_sel_hi:[0,1,0]
	v_fma_mix_f32 v12, v7, v110, v12 op_sel:[0,1,0] op_sel_hi:[0,1,0]
	v_fma_mix_f32 v12, v8, v111, v12 op_sel_hi:[0,1,0]
	v_fma_mix_f32 v12, v9, v111, v12 op_sel:[0,1,0] op_sel_hi:[0,1,0]
	v_fma_mix_f32 v124, v6, v90, v180 op_sel_hi:[0,1,0]
	v_fma_mix_f32 v124, v7, v90, v124 op_sel:[0,1,0] op_sel_hi:[0,1,0]
	v_add_f32_dpp v12, v12, v12 row_ror:1 row_mask:0xf bank_mask:0xf bound_ctrl:1
	v_fma_mix_f32 v124, v8, v91, v124 op_sel_hi:[0,1,0]
	v_fma_mix_f32 v124, v9, v91, v124 op_sel:[0,1,0] op_sel_hi:[0,1,0]
	v_add_f32_dpp v12, v12, v12 row_ror:2 row_mask:0xf bank_mask:0xf bound_ctrl:1
	v_pk_fma_f32 v[48:49], v[118:119], v[68:69], v[6:7] op_sel:[0,1,0]
	v_pk_fma_f32 v[50:51], v[120:121], v[68:69], v[8:9] op_sel:[0,1,0]
	v_add_f32_dpp v12, v12, v12 row_ror:4 row_mask:0xf bank_mask:0xf bound_ctrl:1
	v_add_f32_dpp v102, v102, v102 row_ror:8 row_mask:0xf bank_mask:0xc
	v_add_f32_dpp v102, v55, v55 row_ror:8 row_mask:0xf bank_mask:0x3
	v_add_f32_dpp v103, v103, v103 row_ror:8 row_mask:0xf bank_mask:0xc
	v_add_f32_dpp v12, v12, v12 row_ror:8 row_mask:0xf bank_mask:0xf bound_ctrl:1
	v_pk_fma_f32 v[6:7], v[114:115], v[12:13], v[48:49] op_sel_hi:[1,0,1] neg_lo:[1,0,0] neg_hi:[1,0,0]
	v_pk_fma_f32 v[8:9], v[116:117], v[12:13], v[50:51] op_sel_hi:[1,0,1] neg_lo:[1,0,0] neg_hi:[1,0,0]
	v_pk_mul_f32 v[6:7], v[6:7], v[106:107]
	v_pk_mul_f32 v[8:9], v[8:9], v[108:109]
	ds_read_b128 v[188:191], v10 offset:22784
	ds_read_b128 v[196:199], v10 offset:23296
	ds_read_b128 v[192:195], v10 offset:23040
	s_waitcnt lgkmcnt(3)
	s_nop 0
	v_fma_mix_f32 v12, v6, v142, v180 op_sel_hi:[0,1,0]
	v_fma_mix_f32 v12, v7, v142, v12 op_sel:[0,1,0] op_sel_hi:[0,1,0]
	v_fma_mix_f32 v12, v8, v143, v12 op_sel_hi:[0,1,0]
	v_fma_mix_f32 v12, v9, v143, v12 op_sel:[0,1,0] op_sel_hi:[0,1,0]
	v_fma_mix_f32 v125, v6, v112, v180 op_sel_hi:[0,1,0]
	v_fma_mix_f32 v125, v7, v112, v125 op_sel:[0,1,0] op_sel_hi:[0,1,0]
	v_add_f32_dpp v12, v12, v12 row_ror:1 row_mask:0xf bank_mask:0xf bound_ctrl:1
	v_fma_mix_f32 v125, v8, v113, v125 op_sel_hi:[0,1,0]
	v_fma_mix_f32 v125, v9, v113, v125 op_sel:[0,1,0] op_sel_hi:[0,1,0]
	v_add_f32_dpp v12, v12, v12 row_ror:2 row_mask:0xf bank_mask:0xf bound_ctrl:1
	v_pk_fma_f32 v[48:49], v[150:151], v[70:71], v[6:7] op_sel_hi:[1,0,1]
	v_pk_fma_f32 v[50:51], v[152:153], v[70:71], v[8:9] op_sel_hi:[1,0,1]
	v_add_f32_dpp v12, v12, v12 row_ror:4 row_mask:0xf bank_mask:0xf bound_ctrl:1
	v_add_f32_dpp v103, v56, v56 row_ror:8 row_mask:0xf bank_mask:0x3
	v_add_f32_dpp v104, v104, v104 row_ror:8 row_mask:0xf bank_mask:0xc
	v_add_f32_dpp v104, v57, v57 row_ror:8 row_mask:0xf bank_mask:0x3
	v_add_f32_dpp v12, v12, v12 row_ror:8 row_mask:0xf bank_mask:0xf bound_ctrl:1
	v_pk_fma_f32 v[6:7], v[146:147], v[12:13], v[48:49] op_sel_hi:[1,0,1] neg_lo:[1,0,0] neg_hi:[1,0,0]
	v_pk_fma_f32 v[8:9], v[148:149], v[12:13], v[50:51] op_sel_hi:[1,0,1] neg_lo:[1,0,0] neg_hi:[1,0,0]
	ds_read_b128 v[204:207], v10 offset:23808
	ds_read_b128 v[200:203], v10 offset:23552
	ds_read_b128 v[212:215], v10 offset:24320
	ds_read_b128 v[208:211], v10 offset:24064
	v_fma_mix_f32 v12, v6, v158, v180 op_sel_hi:[0,1,0]
	v_fma_mix_f32 v12, v7, v158, v12 op_sel:[0,1,0] op_sel_hi:[0,1,0]
	v_fma_mix_f32 v12, v8, v159, v12 op_sel_hi:[0,1,0]
	v_fma_mix_f32 v12, v9, v159, v12 op_sel:[0,1,0] op_sel_hi:[0,1,0]
	v_fma_mix_f32 v126, v6, v144, v180 op_sel_hi:[0,1,0]
	v_fma_mix_f32 v126, v7, v144, v126 op_sel:[0,1,0] op_sel_hi:[0,1,0]
	v_add_f32_dpp v12, v12, v12 row_ror:1 row_mask:0xf bank_mask:0xf bound_ctrl:1
	v_fma_mix_f32 v126, v8, v145, v126 op_sel_hi:[0,1,0]
	v_fma_mix_f32 v126, v9, v145, v126 op_sel:[0,1,0] op_sel_hi:[0,1,0]
	v_add_f32_dpp v12, v12, v12 row_ror:2 row_mask:0xf bank_mask:0xf bound_ctrl:1
	v_pk_fma_f32 v[48:49], v[166:167], v[70:71], v[6:7] op_sel:[0,1,0]
	v_pk_fma_f32 v[50:51], v[168:169], v[70:71], v[8:9] op_sel:[0,1,0]
	v_add_f32_dpp v12, v12, v12 row_ror:4 row_mask:0xf bank_mask:0xf bound_ctrl:1
	v_add_f32_dpp v105, v105, v105 row_ror:8 row_mask:0xf bank_mask:0xc
	v_add_f32_dpp v105, v81, v81 row_ror:8 row_mask:0xf bank_mask:0x3
	v_add_f32_dpp v12, v12, v12 row_ror:8 row_mask:0xf bank_mask:0xf bound_ctrl:1
	v_pk_fma_f32 v[6:7], v[162:163], v[12:13], v[48:49] op_sel_hi:[1,0,1] neg_lo:[1,0,0] neg_hi:[1,0,0]
	v_pk_fma_f32 v[8:9], v[164:165], v[12:13], v[50:51] op_sel_hi:[1,0,1] neg_lo:[1,0,0] neg_hi:[1,0,0]
	ds_read_b128 v[20:23], v10 offset:24832
	ds_read_b128 v[28:31], v10 offset:25344
	ds_read_b128 v[24:27], v10 offset:25088
	ds_read_b128 v[66:69], v11 offset:1536
	s_waitcnt lgkmcnt(4)
	s_nop 0
	v_fma_mix_f32 v12, v6, v188, v180 op_sel_hi:[0,1,0]
	v_fma_mix_f32 v12, v7, v188, v12 op_sel:[0,1,0] op_sel_hi:[0,1,0]
	v_fma_mix_f32 v12, v8, v189, v12 op_sel_hi:[0,1,0]
	v_fma_mix_f32 v12, v9, v189, v12 op_sel:[0,1,0] op_sel_hi:[0,1,0]
	v_fma_mix_f32 v127, v6, v160, v180 op_sel_hi:[0,1,0]
	v_fma_mix_f32 v127, v7, v160, v127 op_sel:[0,1,0] op_sel_hi:[0,1,0]
	v_add_f32_dpp v12, v12, v12 row_ror:1 row_mask:0xf bank_mask:0xf bound_ctrl:1
	v_fma_mix_f32 v127, v8, v161, v127 op_sel_hi:[0,1,0]
	v_fma_mix_f32 v127, v9, v161, v127 op_sel:[0,1,0] op_sel_hi:[0,1,0]
	v_add_f32_dpp v12, v12, v12 row_ror:2 row_mask:0xf bank_mask:0xf bound_ctrl:1
	v_pk_fma_f32 v[48:49], v[196:197], v[72:73], v[6:7] op_sel_hi:[1,0,1]
	v_pk_fma_f32 v[50:51], v[198:199], v[72:73], v[8:9] op_sel_hi:[1,0,1]
	v_add_f32_dpp v12, v12, v12 row_ror:4 row_mask:0xf bank_mask:0xf bound_ctrl:1
	v_add_f32_dpp v61, v61, v61 row_ror:8 row_mask:0xf bank_mask:0xc
	v_add_f32_dpp v61, v82, v82 row_ror:8 row_mask:0xf bank_mask:0x3
	v_add_f32_dpp v12, v12, v12 row_ror:8 row_mask:0xf bank_mask:0xf bound_ctrl:1
	v_pk_fma_f32 v[6:7], v[192:193], v[12:13], v[48:49] op_sel_hi:[1,0,1] neg_lo:[1,0,0] neg_hi:[1,0,0]
	v_pk_fma_f32 v[8:9], v[194:195], v[12:13], v[50:51] op_sel_hi:[1,0,1] neg_lo:[1,0,0] neg_hi:[1,0,0]
	ds_read_b128 v[36:39], v10 offset:25856
	ds_read_b128 v[44:47], v10 offset:26368
	ds_read_b128 v[40:43], v10 offset:26112
	v_fma_mix_f32 v12, v6, v204, v180 op_sel_hi:[0,1,0]
	v_fma_mix_f32 v12, v7, v204, v12 op_sel:[0,1,0] op_sel_hi:[0,1,0]
	v_fma_mix_f32 v12, v8, v205, v12 op_sel_hi:[0,1,0]
	v_fma_mix_f32 v12, v9, v205, v12 op_sel:[0,1,0] op_sel_hi:[0,1,0]
	v_fma_mix_f32 v128, v6, v190, v180 op_sel_hi:[0,1,0]
	v_fma_mix_f32 v128, v7, v190, v128 op_sel:[0,1,0] op_sel_hi:[0,1,0]
	v_add_f32_dpp v12, v12, v12 row_ror:1 row_mask:0xf bank_mask:0xf bound_ctrl:1
	v_fma_mix_f32 v128, v8, v191, v128 op_sel_hi:[0,1,0]
	v_fma_mix_f32 v128, v9, v191, v128 op_sel:[0,1,0] op_sel_hi:[0,1,0]
	v_add_f32_dpp v12, v12, v12 row_ror:2 row_mask:0xf bank_mask:0xf bound_ctrl:1
	v_pk_fma_f32 v[48:49], v[212:213], v[72:73], v[6:7] op_sel:[0,1,0]
	v_pk_fma_f32 v[50:51], v[214:215], v[72:73], v[8:9] op_sel:[0,1,0]
	v_add_f32_dpp v12, v12, v12 row_ror:4 row_mask:0xf bank_mask:0xf bound_ctrl:1
	v_add_f32_dpp v103, v103, v103 row_ror:4 row_mask:0xf bank_mask:0xa
	v_add_f32_dpp v103, v83, v83 row_ror:12 row_mask:0xf bank_mask:0x5
	v_add_f32_dpp v104, v104, v104 row_ror:4 row_mask:0xf bank_mask:0xa
	v_add_f32_dpp v12, v12, v12 row_ror:8 row_mask:0xf bank_mask:0xf bound_ctrl:1
	v_pk_fma_f32 v[6:7], v[208:209], v[12:13], v[48:49] op_sel_hi:[1,0,1] neg_lo:[1,0,0] neg_hi:[1,0,0]
	v_pk_fma_f32 v[8:9], v[210:211], v[12:13], v[50:51] op_sel_hi:[1,0,1] neg_lo:[1,0,0] neg_hi:[1,0,0]
	v_pk_mul_f32 v[6:7], v[6:7], v[200:201]
	v_pk_mul_f32 v[8:9], v[8:9], v[202:203]
	ds_read_b128 v[88:91], v10 offset:26880
	ds_read_b128 v[96:99], v10 offset:27392
	ds_read_b128 v[92:95], v10 offset:27136
	s_waitcnt lgkmcnt(3)
	s_nop 0
	v_fma_mix_f32 v12, v6, v20, v180 op_sel_hi:[0,1,0]
	v_fma_mix_f32 v12, v7, v20, v12 op_sel:[0,1,0] op_sel_hi:[0,1,0]
	v_fma_mix_f32 v12, v8, v21, v12 op_sel_hi:[0,1,0]
	v_fma_mix_f32 v12, v9, v21, v12 op_sel:[0,1,0] op_sel_hi:[0,1,0]
	v_fma_mix_f32 v129, v6, v206, v180 op_sel_hi:[0,1,0]
	v_fma_mix_f32 v129, v7, v206, v129 op_sel:[0,1,0] op_sel_hi:[0,1,0]
	v_add_f32_dpp v12, v12, v12 row_ror:1 row_mask:0xf bank_mask:0xf bound_ctrl:1
	v_fma_mix_f32 v129, v8, v207, v129 op_sel_hi:[0,1,0]
	v_fma_mix_f32 v129, v9, v207, v129 op_sel:[0,1,0] op_sel_hi:[0,1,0]
	v_add_f32_dpp v12, v12, v12 row_ror:2 row_mask:0xf bank_mask:0xf bound_ctrl:1
	v_pk_fma_f32 v[48:49], v[28:29], v[66:67], v[6:7] op_sel_hi:[1,0,1]
	v_pk_fma_f32 v[50:51], v[30:31], v[66:67], v[8:9] op_sel_hi:[1,0,1]
	v_add_f32_dpp v12, v12, v12 row_ror:4 row_mask:0xf bank_mask:0xf bound_ctrl:1
	v_add_f32_dpp v104, v100, v100 row_ror:12 row_mask:0xf bank_mask:0x5
	v_add_f32_dpp v105, v105, v105 row_ror:4 row_mask:0xf bank_mask:0xa
	v_add_f32_dpp v105, v101, v101 row_ror:12 row_mask:0xf bank_mask:0x5
	v_add_f32_dpp v12, v12, v12 row_ror:8 row_mask:0xf bank_mask:0xf bound_ctrl:1
	v_pk_fma_f32 v[6:7], v[24:25], v[12:13], v[48:49] op_sel_hi:[1,0,1] neg_lo:[1,0,0] neg_hi:[1,0,0]
	v_pk_fma_f32 v[8:9], v[26:27], v[12:13], v[50:51] op_sel_hi:[1,0,1] neg_lo:[1,0,0] neg_hi:[1,0,0]
	ds_read_b128 v[110:113], v10 offset:27904
	ds_read_b128 v[106:109], v10 offset:27648
	ds_read_b128 v[118:121], v10 offset:28416
	ds_read_b128 v[114:117], v10 offset:28160
	v_fma_mix_f32 v12, v6, v36, v180 op_sel_hi:[0,1,0]
	v_fma_mix_f32 v12, v7, v36, v12 op_sel:[0,1,0] op_sel_hi:[0,1,0]
	v_fma_mix_f32 v12, v8, v37, v12 op_sel_hi:[0,1,0]
	v_fma_mix_f32 v12, v9, v37, v12 op_sel:[0,1,0] op_sel_hi:[0,1,0]
	v_fma_mix_f32 v130, v6, v22, v180 op_sel_hi:[0,1,0]
	v_fma_mix_f32 v130, v7, v22, v130 op_sel:[0,1,0] op_sel_hi:[0,1,0]
	v_add_f32_dpp v12, v12, v12 row_ror:1 row_mask:0xf bank_mask:0xf bound_ctrl:1
	v_fma_mix_f32 v130, v8, v23, v130 op_sel_hi:[0,1,0]
	v_fma_mix_f32 v130, v9, v23, v130 op_sel:[0,1,0] op_sel_hi:[0,1,0]
	v_add_f32_dpp v12, v12, v12 row_ror:2 row_mask:0xf bank_mask:0xf bound_ctrl:1
	v_pk_fma_f32 v[48:49], v[44:45], v[66:67], v[6:7] op_sel:[0,1,0]
	v_pk_fma_f32 v[50:51], v[46:47], v[66:67], v[8:9] op_sel:[0,1,0]
	v_add_f32_dpp v12, v12, v12 row_ror:4 row_mask:0xf bank_mask:0xf bound_ctrl:1
	v_add_f32_dpp v61, v61, v61 row_ror:4 row_mask:0xf bank_mask:0xa
	v_add_f32_dpp v61, v102, v102 row_ror:12 row_mask:0xf bank_mask:0x5
	v_add_f32_dpp v12, v12, v12 row_ror:8 row_mask:0xf bank_mask:0xf bound_ctrl:1
	v_pk_fma_f32 v[6:7], v[40:41], v[12:13], v[48:49] op_sel_hi:[1,0,1] neg_lo:[1,0,0] neg_hi:[1,0,0]
	v_pk_fma_f32 v[8:9], v[42:43], v[12:13], v[50:51] op_sel_hi:[1,0,1] neg_lo:[1,0,0] neg_hi:[1,0,0]
	ds_read_b128 v[142:145], v10 offset:28928
	ds_read_b128 v[150:153], v10 offset:29440
	ds_read_b128 v[146:149], v10 offset:29184
	ds_read_b128 v[70:73], v11 offset:1792
	s_waitcnt lgkmcnt(4)
	s_nop 0
	v_fma_mix_f32 v12, v6, v88, v180 op_sel_hi:[0,1,0]
	v_fma_mix_f32 v12, v7, v88, v12 op_sel:[0,1,0] op_sel_hi:[0,1,0]
	v_fma_mix_f32 v12, v8, v89, v12 op_sel_hi:[0,1,0]
	v_fma_mix_f32 v12, v9, v89, v12 op_sel:[0,1,0] op_sel_hi:[0,1,0]
	v_fma_mix_f32 v131, v6, v38, v180 op_sel_hi:[0,1,0]
	v_fma_mix_f32 v131, v7, v38, v131 op_sel:[0,1,0] op_sel_hi:[0,1,0]
	v_add_f32_dpp v12, v12, v12 row_ror:1 row_mask:0xf bank_mask:0xf bound_ctrl:1
	v_fma_mix_f32 v131, v8, v39, v131 op_sel_hi:[0,1,0]
	v_fma_mix_f32 v131, v9, v39, v131 op_sel:[0,1,0] op_sel_hi:[0,1,0]
	v_add_f32_dpp v12, v12, v12 row_ror:2 row_mask:0xf bank_mask:0xf bound_ctrl:1
	v_pk_fma_f32 v[48:49], v[96:97], v[68:69], v[6:7] op_sel_hi:[1,0,1]
	v_pk_fma_f32 v[50:51], v[98:99], v[68:69], v[8:9] op_sel_hi:[1,0,1]
	v_add_f32_dpp v12, v12, v12 row_ror:4 row_mask:0xf bank_mask:0xf bound_ctrl:1
	v_cndmask_b32_e64 v62, v105, v103, s[38:39]
	v_cndmask_b32_e64 v63, v103, v105, s[38:39]
	v_add_f32_dpp v12, v12, v12 row_ror:8 row_mask:0xf bank_mask:0xf bound_ctrl:1
	v_pk_fma_f32 v[6:7], v[92:93], v[12:13], v[48:49] op_sel_hi:[1,0,1] neg_lo:[1,0,0] neg_hi:[1,0,0]
	v_pk_fma_f32 v[8:9], v[94:95], v[12:13], v[50:51] op_sel_hi:[1,0,1] neg_lo:[1,0,0] neg_hi:[1,0,0]
	ds_read_b128 v[158:161], v10 offset:29952
	ds_read_b128 v[166:169], v10 offset:30464
	ds_read_b128 v[162:165], v10 offset:30208
	v_fma_mix_f32 v12, v6, v110, v180 op_sel_hi:[0,1,0]
	v_fma_mix_f32 v12, v7, v110, v12 op_sel:[0,1,0] op_sel_hi:[0,1,0]
	v_fma_mix_f32 v12, v8, v111, v12 op_sel_hi:[0,1,0]
	v_fma_mix_f32 v12, v9, v111, v12 op_sel:[0,1,0] op_sel_hi:[0,1,0]
	v_fma_mix_f32 v132, v6, v90, v180 op_sel_hi:[0,1,0]
	v_fma_mix_f32 v132, v7, v90, v132 op_sel:[0,1,0] op_sel_hi:[0,1,0]
	v_add_f32_dpp v12, v12, v12 row_ror:1 row_mask:0xf bank_mask:0xf bound_ctrl:1
	v_fma_mix_f32 v132, v8, v91, v132 op_sel_hi:[0,1,0]
	v_fma_mix_f32 v132, v9, v91, v132 op_sel:[0,1,0] op_sel_hi:[0,1,0]
	v_add_f32_dpp v12, v12, v12 row_ror:2 row_mask:0xf bank_mask:0xf bound_ctrl:1
	v_pk_fma_f32 v[48:49], v[118:119], v[68:69], v[6:7] op_sel:[0,1,0]
	v_pk_fma_f32 v[50:51], v[120:121], v[68:69], v[8:9] op_sel:[0,1,0]
	v_add_f32_dpp v12, v12, v12 row_ror:4 row_mask:0xf bank_mask:0xf bound_ctrl:1
	v_cndmask_b32_e64 v64, v61, v104, s[38:39]
	v_cndmask_b32_e64 v65, v104, v61, s[38:39]
	v_add_f32_dpp v12, v12, v12 row_ror:8 row_mask:0xf bank_mask:0xf bound_ctrl:1
	v_pk_fma_f32 v[6:7], v[114:115], v[12:13], v[48:49] op_sel_hi:[1,0,1] neg_lo:[1,0,0] neg_hi:[1,0,0]
	v_pk_fma_f32 v[8:9], v[116:117], v[12:13], v[50:51] op_sel_hi:[1,0,1] neg_lo:[1,0,0] neg_hi:[1,0,0]
	v_pk_mul_f32 v[6:7], v[6:7], v[106:107]
	v_pk_mul_f32 v[8:9], v[8:9], v[108:109]
	ds_read_b128 v[188:191], v10 offset:30976
	ds_read_b128 v[196:199], v10 offset:31488
	ds_read_b128 v[192:195], v10 offset:31232
	s_waitcnt lgkmcnt(3)
	s_nop 0
	v_fma_mix_f32 v12, v6, v142, v180 op_sel_hi:[0,1,0]
	v_fma_mix_f32 v12, v7, v142, v12 op_sel:[0,1,0] op_sel_hi:[0,1,0]
	v_fma_mix_f32 v12, v8, v143, v12 op_sel_hi:[0,1,0]
	v_fma_mix_f32 v12, v9, v143, v12 op_sel:[0,1,0] op_sel_hi:[0,1,0]
	v_fma_mix_f32 v133, v6, v112, v180 op_sel_hi:[0,1,0]
	v_fma_mix_f32 v133, v7, v112, v133 op_sel:[0,1,0] op_sel_hi:[0,1,0]
	v_add_f32_dpp v12, v12, v12 row_ror:1 row_mask:0xf bank_mask:0xf bound_ctrl:1
	v_fma_mix_f32 v133, v8, v113, v133 op_sel_hi:[0,1,0]
	v_fma_mix_f32 v133, v9, v113, v133 op_sel:[0,1,0] op_sel_hi:[0,1,0]
	v_add_f32_dpp v12, v12, v12 row_ror:2 row_mask:0xf bank_mask:0xf bound_ctrl:1
	v_pk_fma_f32 v[48:49], v[150:151], v[70:71], v[6:7] op_sel_hi:[1,0,1]
	v_pk_fma_f32 v[50:51], v[152:153], v[70:71], v[8:9] op_sel_hi:[1,0,1]
	v_add_f32_dpp v12, v12, v12 row_ror:4 row_mask:0xf bank_mask:0xf bound_ctrl:1
	v_add_f32_dpp v62, v63, v62 quad_perm:[2,3,0,1] row_mask:0xf bank_mask:0xf bound_ctrl:1
	v_add_f32_dpp v63, v65, v64 quad_perm:[2,3,0,1] row_mask:0xf bank_mask:0xf bound_ctrl:1
	v_add_f32_dpp v12, v12, v12 row_ror:8 row_mask:0xf bank_mask:0xf bound_ctrl:1
	v_pk_fma_f32 v[6:7], v[146:147], v[12:13], v[48:49] op_sel_hi:[1,0,1] neg_lo:[1,0,0] neg_hi:[1,0,0]
	v_pk_fma_f32 v[8:9], v[148:149], v[12:13], v[50:51] op_sel_hi:[1,0,1] neg_lo:[1,0,0] neg_hi:[1,0,0]
	ds_read_b128 v[204:207], v10 offset:32000
	ds_read_b128 v[200:203], v10 offset:31744
	ds_read_b128 v[212:215], v10 offset:32512
	ds_read_b128 v[208:211], v10 offset:32256
	v_fma_mix_f32 v12, v6, v158, v180 op_sel_hi:[0,1,0]
	v_fma_mix_f32 v12, v7, v158, v12 op_sel:[0,1,0] op_sel_hi:[0,1,0]
	v_fma_mix_f32 v12, v8, v159, v12 op_sel_hi:[0,1,0]
	v_fma_mix_f32 v12, v9, v159, v12 op_sel:[0,1,0] op_sel_hi:[0,1,0]
	v_fma_mix_f32 v134, v6, v144, v180 op_sel_hi:[0,1,0]
	v_fma_mix_f32 v134, v7, v144, v134 op_sel:[0,1,0] op_sel_hi:[0,1,0]
	v_add_f32_dpp v12, v12, v12 row_ror:1 row_mask:0xf bank_mask:0xf bound_ctrl:1
	v_fma_mix_f32 v134, v8, v145, v134 op_sel_hi:[0,1,0]
	v_fma_mix_f32 v134, v9, v145, v134 op_sel:[0,1,0] op_sel_hi:[0,1,0]
	v_add_f32_dpp v12, v12, v12 row_ror:2 row_mask:0xf bank_mask:0xf bound_ctrl:1
	v_pk_fma_f32 v[48:49], v[166:167], v[70:71], v[6:7] op_sel:[0,1,0]
	v_pk_fma_f32 v[50:51], v[168:169], v[70:71], v[8:9] op_sel:[0,1,0]
	v_add_f32_dpp v12, v12, v12 row_ror:4 row_mask:0xf bank_mask:0xf bound_ctrl:1
	v_cndmask_b32_e64 v65, v63, v62, s[40:41]
	v_cndmask_b32_e64 v62, v62, v63, s[40:41]
	v_add_f32_dpp v12, v12, v12 row_ror:8 row_mask:0xf bank_mask:0xf bound_ctrl:1
	v_pk_fma_f32 v[6:7], v[162:163], v[12:13], v[48:49] op_sel_hi:[1,0,1] neg_lo:[1,0,0] neg_hi:[1,0,0]
	v_pk_fma_f32 v[8:9], v[164:165], v[12:13], v[50:51] op_sel_hi:[1,0,1] neg_lo:[1,0,0] neg_hi:[1,0,0]
	ds_read_b128 v[20:23], v10 offset:33024
	ds_read_b128 v[28:31], v10 offset:33536
	ds_read_b128 v[24:27], v10 offset:33280
	ds_read_b128 v[66:69], v11 offset:2048
	s_waitcnt lgkmcnt(4)
	s_nop 0
	v_fma_mix_f32 v12, v6, v188, v180 op_sel_hi:[0,1,0]
	v_fma_mix_f32 v12, v7, v188, v12 op_sel:[0,1,0] op_sel_hi:[0,1,0]
	v_fma_mix_f32 v12, v8, v189, v12 op_sel_hi:[0,1,0]
	v_fma_mix_f32 v12, v9, v189, v12 op_sel:[0,1,0] op_sel_hi:[0,1,0]
	v_fma_mix_f32 v135, v6, v160, v180 op_sel_hi:[0,1,0]
	v_fma_mix_f32 v135, v7, v160, v135 op_sel:[0,1,0] op_sel_hi:[0,1,0]
	v_add_f32_dpp v12, v12, v12 row_ror:1 row_mask:0xf bank_mask:0xf bound_ctrl:1
	v_fma_mix_f32 v135, v8, v161, v135 op_sel_hi:[0,1,0]
	v_fma_mix_f32 v135, v9, v161, v135 op_sel:[0,1,0] op_sel_hi:[0,1,0]
	v_add_f32_dpp v12, v12, v12 row_ror:2 row_mask:0xf bank_mask:0xf bound_ctrl:1
	v_pk_fma_f32 v[48:49], v[196:197], v[72:73], v[6:7] op_sel_hi:[1,0,1]
	v_pk_fma_f32 v[50:51], v[198:199], v[72:73], v[8:9] op_sel_hi:[1,0,1]
	v_add_f32_dpp v12, v12, v12 row_ror:4 row_mask:0xf bank_mask:0xf bound_ctrl:1
	v_add_f32_dpp v62, v62, v65 quad_perm:[1,0,3,2] row_mask:0xf bank_mask:0xf bound_ctrl:1
	v_cvt_pk_bf16_f32 v62, v62, v62
	v_add_f32_dpp v12, v12, v12 row_ror:8 row_mask:0xf bank_mask:0xf bound_ctrl:1
	v_pk_fma_f32 v[6:7], v[192:193], v[12:13], v[48:49] op_sel_hi:[1,0,1] neg_lo:[1,0,0] neg_hi:[1,0,0]
	v_pk_fma_f32 v[8:9], v[194:195], v[12:13], v[50:51] op_sel_hi:[1,0,1] neg_lo:[1,0,0] neg_hi:[1,0,0]
	ds_read_b128 v[36:39], v10 offset:34048
	ds_read_b128 v[44:47], v10 offset:34560
	ds_read_b128 v[40:43], v10 offset:34304
	v_fma_mix_f32 v12, v6, v204, v180 op_sel_hi:[0,1,0]
	v_fma_mix_f32 v12, v7, v204, v12 op_sel:[0,1,0] op_sel_hi:[0,1,0]
	v_fma_mix_f32 v12, v8, v205, v12 op_sel_hi:[0,1,0]
	v_fma_mix_f32 v12, v9, v205, v12 op_sel:[0,1,0] op_sel_hi:[0,1,0]
	v_fma_mix_f32 v136, v6, v190, v180 op_sel_hi:[0,1,0]
	v_fma_mix_f32 v136, v7, v190, v136 op_sel:[0,1,0] op_sel_hi:[0,1,0]
	v_add_f32_dpp v12, v12, v12 row_ror:1 row_mask:0xf bank_mask:0xf bound_ctrl:1
	v_fma_mix_f32 v136, v8, v191, v136 op_sel_hi:[0,1,0]
	v_fma_mix_f32 v136, v9, v191, v136 op_sel:[0,1,0] op_sel_hi:[0,1,0]
	v_add_f32_dpp v12, v12, v12 row_ror:2 row_mask:0xf bank_mask:0xf bound_ctrl:1
	v_pk_fma_f32 v[48:49], v[212:213], v[72:73], v[6:7] op_sel:[0,1,0]
	v_pk_fma_f32 v[50:51], v[214:215], v[72:73], v[8:9] op_sel:[0,1,0]
	v_add_f32_dpp v12, v12, v12 row_ror:4 row_mask:0xf bank_mask:0xf bound_ctrl:1
	global_store_short v[2:3], v62, off
	v_lshl_add_u64 v[2:3], v[2:3], 0, s[84:85]
	v_add_f32_dpp v12, v12, v12 row_ror:8 row_mask:0xf bank_mask:0xf bound_ctrl:1
	v_pk_fma_f32 v[6:7], v[208:209], v[12:13], v[48:49] op_sel_hi:[1,0,1] neg_lo:[1,0,0] neg_hi:[1,0,0]
	v_pk_fma_f32 v[8:9], v[210:211], v[12:13], v[50:51] op_sel_hi:[1,0,1] neg_lo:[1,0,0] neg_hi:[1,0,0]
	v_pk_mul_f32 v[6:7], v[6:7], v[200:201]
	v_pk_mul_f32 v[8:9], v[8:9], v[202:203]
	ds_read_b128 v[88:91], v10 offset:35072
	ds_read_b128 v[96:99], v10 offset:35584
	ds_read_b128 v[92:95], v10 offset:35328
	s_waitcnt lgkmcnt(3)
	s_nop 0
	v_fma_mix_f32 v12, v6, v20, v180 op_sel_hi:[0,1,0]
	v_fma_mix_f32 v12, v7, v20, v12 op_sel:[0,1,0] op_sel_hi:[0,1,0]
	v_fma_mix_f32 v12, v8, v21, v12 op_sel_hi:[0,1,0]
	v_fma_mix_f32 v12, v9, v21, v12 op_sel:[0,1,0] op_sel_hi:[0,1,0]
	v_fma_mix_f32 v137, v6, v206, v180 op_sel_hi:[0,1,0]
	v_fma_mix_f32 v137, v7, v206, v137 op_sel:[0,1,0] op_sel_hi:[0,1,0]
	v_add_f32_dpp v12, v12, v12 row_ror:1 row_mask:0xf bank_mask:0xf bound_ctrl:1
	v_fma_mix_f32 v137, v8, v207, v137 op_sel_hi:[0,1,0]
	v_fma_mix_f32 v137, v9, v207, v137 op_sel:[0,1,0] op_sel_hi:[0,1,0]
	v_add_f32_dpp v12, v12, v12 row_ror:2 row_mask:0xf bank_mask:0xf bound_ctrl:1
	v_pk_fma_f32 v[48:49], v[28:29], v[66:67], v[6:7] op_sel_hi:[1,0,1]
	v_pk_fma_f32 v[50:51], v[30:31], v[66:67], v[8:9] op_sel_hi:[1,0,1]
	v_add_f32_dpp v12, v12, v12 row_ror:4 row_mask:0xf bank_mask:0xf bound_ctrl:1
	s_nop 1
	s_nop 0
	v_add_f32_dpp v12, v12, v12 row_ror:8 row_mask:0xf bank_mask:0xf bound_ctrl:1
	v_pk_fma_f32 v[6:7], v[24:25], v[12:13], v[48:49] op_sel_hi:[1,0,1] neg_lo:[1,0,0] neg_hi:[1,0,0]
	v_pk_fma_f32 v[8:9], v[26:27], v[12:13], v[50:51] op_sel_hi:[1,0,1] neg_lo:[1,0,0] neg_hi:[1,0,0]
	ds_read_b128 v[110:113], v10 offset:36096
	ds_read_b128 v[106:109], v10 offset:35840
	ds_read_b128 v[118:121], v10 offset:36608
	ds_read_b128 v[114:117], v10 offset:36352
	v_fma_mix_f32 v12, v6, v36, v180 op_sel_hi:[0,1,0]
	v_fma_mix_f32 v12, v7, v36, v12 op_sel:[0,1,0] op_sel_hi:[0,1,0]
	v_fma_mix_f32 v12, v8, v37, v12 op_sel_hi:[0,1,0]
	v_fma_mix_f32 v12, v9, v37, v12 op_sel:[0,1,0] op_sel_hi:[0,1,0]
	v_fma_mix_f32 v52, v6, v22, v180 op_sel_hi:[0,1,0]
	v_fma_mix_f32 v52, v7, v22, v52 op_sel:[0,1,0] op_sel_hi:[0,1,0]
	v_add_f32_dpp v12, v12, v12 row_ror:1 row_mask:0xf bank_mask:0xf bound_ctrl:1
	v_fma_mix_f32 v52, v8, v23, v52 op_sel_hi:[0,1,0]
	v_fma_mix_f32 v52, v9, v23, v52 op_sel:[0,1,0] op_sel_hi:[0,1,0]
	v_add_f32_dpp v12, v12, v12 row_ror:2 row_mask:0xf bank_mask:0xf bound_ctrl:1
	v_pk_fma_f32 v[48:49], v[44:45], v[66:67], v[6:7] op_sel:[0,1,0]
	v_pk_fma_f32 v[50:51], v[46:47], v[66:67], v[8:9] op_sel:[0,1,0]
	v_add_f32_dpp v12, v12, v12 row_ror:4 row_mask:0xf bank_mask:0xf bound_ctrl:1
	v_add_f32_dpp v130, v130, v130 row_ror:8 row_mask:0xf bank_mask:0xc
	v_add_f32_dpp v130, v122, v122 row_ror:8 row_mask:0xf bank_mask:0x3
	v_add_f32_dpp v131, v131, v131 row_ror:8 row_mask:0xf bank_mask:0xc
	v_add_f32_dpp v12, v12, v12 row_ror:8 row_mask:0xf bank_mask:0xf bound_ctrl:1
	v_pk_fma_f32 v[6:7], v[40:41], v[12:13], v[48:49] op_sel_hi:[1,0,1] neg_lo:[1,0,0] neg_hi:[1,0,0]
	v_pk_fma_f32 v[8:9], v[42:43], v[12:13], v[50:51] op_sel_hi:[1,0,1] neg_lo:[1,0,0] neg_hi:[1,0,0]
	ds_read_b128 v[142:145], v10 offset:37120
	ds_read_b128 v[150:153], v10 offset:37632
	ds_read_b128 v[146:149], v10 offset:37376
	ds_read_b128 v[70:73], v11 offset:2304
	s_waitcnt lgkmcnt(4)
	s_nop 0
	v_fma_mix_f32 v12, v6, v88, v180 op_sel_hi:[0,1,0]
	v_fma_mix_f32 v12, v7, v88, v12 op_sel:[0,1,0] op_sel_hi:[0,1,0]
	v_fma_mix_f32 v12, v8, v89, v12 op_sel_hi:[0,1,0]
	v_fma_mix_f32 v12, v9, v89, v12 op_sel:[0,1,0] op_sel_hi:[0,1,0]
	v_fma_mix_f32 v53, v6, v38, v180 op_sel_hi:[0,1,0]
	v_fma_mix_f32 v53, v7, v38, v53 op_sel:[0,1,0] op_sel_hi:[0,1,0]
	v_add_f32_dpp v12, v12, v12 row_ror:1 row_mask:0xf bank_mask:0xf bound_ctrl:1
	v_fma_mix_f32 v53, v8, v39, v53 op_sel_hi:[0,1,0]
	v_fma_mix_f32 v53, v9, v39, v53 op_sel:[0,1,0] op_sel_hi:[0,1,0]
	v_add_f32_dpp v12, v12, v12 row_ror:2 row_mask:0xf bank_mask:0xf bound_ctrl:1
	v_pk_fma_f32 v[48:49], v[96:97], v[68:69], v[6:7] op_sel_hi:[1,0,1]
	v_pk_fma_f32 v[50:51], v[98:99], v[68:69], v[8:9] op_sel_hi:[1,0,1]
	v_add_f32_dpp v12, v12, v12 row_ror:4 row_mask:0xf bank_mask:0xf bound_ctrl:1
	v_add_f32_dpp v131, v123, v123 row_ror:8 row_mask:0xf bank_mask:0x3
	v_add_f32_dpp v132, v132, v132 row_ror:8 row_mask:0xf bank_mask:0xc
	v_add_f32_dpp v132, v124, v124 row_ror:8 row_mask:0xf bank_mask:0x3
	v_add_f32_dpp v12, v12, v12 row_ror:8 row_mask:0xf bank_mask:0xf bound_ctrl:1
	v_pk_fma_f32 v[6:7], v[92:93], v[12:13], v[48:49] op_sel_hi:[1,0,1] neg_lo:[1,0,0] neg_hi:[1,0,0]
	v_pk_fma_f32 v[8:9], v[94:95], v[12:13], v[50:51] op_sel_hi:[1,0,1] neg_lo:[1,0,0] neg_hi:[1,0,0]
	ds_read_b128 v[158:161], v10 offset:38144
	ds_read_b128 v[166:169], v10 offset:38656
	ds_read_b128 v[162:165], v10 offset:38400
	v_fma_mix_f32 v12, v6, v110, v180 op_sel_hi:[0,1,0]
	v_fma_mix_f32 v12, v7, v110, v12 op_sel:[0,1,0] op_sel_hi:[0,1,0]
	v_fma_mix_f32 v12, v8, v111, v12 op_sel_hi:[0,1,0]
	v_fma_mix_f32 v12, v9, v111, v12 op_sel:[0,1,0] op_sel_hi:[0,1,0]
	v_fma_mix_f32 v54, v6, v90, v180 op_sel_hi:[0,1,0]
	v_fma_mix_f32 v54, v7, v90, v54 op_sel:[0,1,0] op_sel_hi:[0,1,0]
	v_add_f32_dpp v12, v12, v12 row_ror:1 row_mask:0xf bank_mask:0xf bound_ctrl:1
	v_fma_mix_f32 v54, v8, v91, v54 op_sel_hi:[0,1,0]
	v_fma_mix_f32 v54, v9, v91, v54 op_sel:[0,1,0] op_sel_hi:[0,1,0]
	v_add_f32_dpp v12, v12, v12 row_ror:2 row_mask:0xf bank_mask:0xf bound_ctrl:1
	v_pk_fma_f32 v[48:49], v[118:119], v[68:69], v[6:7] op_sel:[0,1,0]
	v_pk_fma_f32 v[50:51], v[120:121], v[68:69], v[8:9] op_sel:[0,1,0]
	v_add_f32_dpp v12, v12, v12 row_ror:4 row_mask:0xf bank_mask:0xf bound_ctrl:1
	v_add_f32_dpp v133, v133, v133 row_ror:8 row_mask:0xf bank_mask:0xc
	v_add_f32_dpp v133, v125, v125 row_ror:8 row_mask:0xf bank_mask:0x3
	v_add_f32_dpp v134, v134, v134 row_ror:8 row_mask:0xf bank_mask:0xc
	v_add_f32_dpp v12, v12, v12 row_ror:8 row_mask:0xf bank_mask:0xf bound_ctrl:1
	v_pk_fma_f32 v[6:7], v[114:115], v[12:13], v[48:49] op_sel_hi:[1,0,1] neg_lo:[1,0,0] neg_hi:[1,0,0]
	v_pk_fma_f32 v[8:9], v[116:117], v[12:13], v[50:51] op_sel_hi:[1,0,1] neg_lo:[1,0,0] neg_hi:[1,0,0]
	v_pk_mul_f32 v[6:7], v[6:7], v[106:107]
	v_pk_mul_f32 v[8:9], v[8:9], v[108:109]
	ds_read_b128 v[188:191], v10 offset:39168
	ds_read_b128 v[196:199], v10 offset:39680
	ds_read_b128 v[192:195], v10 offset:39424
	s_waitcnt lgkmcnt(3)
	s_nop 0
	v_fma_mix_f32 v12, v6, v142, v180 op_sel_hi:[0,1,0]
	v_fma_mix_f32 v12, v7, v142, v12 op_sel:[0,1,0] op_sel_hi:[0,1,0]
	v_fma_mix_f32 v12, v8, v143, v12 op_sel_hi:[0,1,0]
	v_fma_mix_f32 v12, v9, v143, v12 op_sel:[0,1,0] op_sel_hi:[0,1,0]
	v_fma_mix_f32 v55, v6, v112, v180 op_sel_hi:[0,1,0]
	v_fma_mix_f32 v55, v7, v112, v55 op_sel:[0,1,0] op_sel_hi:[0,1,0]
	v_add_f32_dpp v12, v12, v12 row_ror:1 row_mask:0xf bank_mask:0xf bound_ctrl:1
	v_fma_mix_f32 v55, v8, v113, v55 op_sel_hi:[0,1,0]
	v_fma_mix_f32 v55, v9, v113, v55 op_sel:[0,1,0] op_sel_hi:[0,1,0]
	v_add_f32_dpp v12, v12, v12 row_ror:2 row_mask:0xf bank_mask:0xf bound_ctrl:1
	v_pk_fma_f32 v[48:49], v[150:151], v[70:71], v[6:7] op_sel_hi:[1,0,1]
	v_pk_fma_f32 v[50:51], v[152:153], v[70:71], v[8:9] op_sel_hi:[1,0,1]
	v_add_f32_dpp v12, v12, v12 row_ror:4 row_mask:0xf bank_mask:0xf bound_ctrl:1
	v_add_f32_dpp v134, v126, v126 row_ror:8 row_mask:0xf bank_mask:0x3
	v_add_f32_dpp v135, v135, v135 row_ror:8 row_mask:0xf bank_mask:0xc
	v_add_f32_dpp v135, v127, v127 row_ror:8 row_mask:0xf bank_mask:0x3
	v_add_f32_dpp v12, v12, v12 row_ror:8 row_mask:0xf bank_mask:0xf bound_ctrl:1
	v_pk_fma_f32 v[6:7], v[146:147], v[12:13], v[48:49] op_sel_hi:[1,0,1] neg_lo:[1,0,0] neg_hi:[1,0,0]
	v_pk_fma_f32 v[8:9], v[148:149], v[12:13], v[50:51] op_sel_hi:[1,0,1] neg_lo:[1,0,0] neg_hi:[1,0,0]
	ds_read_b128 v[204:207], v10 offset:40192
	ds_read_b128 v[200:203], v10 offset:39936
	ds_read_b128 v[212:215], v10 offset:40704
	ds_read_b128 v[208:211], v10 offset:40448
	v_fma_mix_f32 v12, v6, v158, v180 op_sel_hi:[0,1,0]
	v_fma_mix_f32 v12, v7, v158, v12 op_sel:[0,1,0] op_sel_hi:[0,1,0]
	v_fma_mix_f32 v12, v8, v159, v12 op_sel_hi:[0,1,0]
	v_fma_mix_f32 v12, v9, v159, v12 op_sel:[0,1,0] op_sel_hi:[0,1,0]
	v_fma_mix_f32 v56, v6, v144, v180 op_sel_hi:[0,1,0]
	v_fma_mix_f32 v56, v7, v144, v56 op_sel:[0,1,0] op_sel_hi:[0,1,0]
	v_add_f32_dpp v12, v12, v12 row_ror:1 row_mask:0xf bank_mask:0xf bound_ctrl:1
	v_fma_mix_f32 v56, v8, v145, v56 op_sel_hi:[0,1,0]
	v_fma_mix_f32 v56, v9, v145, v56 op_sel:[0,1,0] op_sel_hi:[0,1,0]
	v_add_f32_dpp v12, v12, v12 row_ror:2 row_mask:0xf bank_mask:0xf bound_ctrl:1
	v_pk_fma_f32 v[48:49], v[166:167], v[70:71], v[6:7] op_sel:[0,1,0]
	v_pk_fma_f32 v[50:51], v[168:169], v[70:71], v[8:9] op_sel:[0,1,0]
	v_add_f32_dpp v12, v12, v12 row_ror:4 row_mask:0xf bank_mask:0xf bound_ctrl:1
	v_add_f32_dpp v136, v136, v136 row_ror:8 row_mask:0xf bank_mask:0xc
	v_add_f32_dpp v136, v128, v128 row_ror:8 row_mask:0xf bank_mask:0x3
	v_add_f32_dpp v12, v12, v12 row_ror:8 row_mask:0xf bank_mask:0xf bound_ctrl:1
	v_pk_fma_f32 v[6:7], v[162:163], v[12:13], v[48:49] op_sel_hi:[1,0,1] neg_lo:[1,0,0] neg_hi:[1,0,0]
	v_pk_fma_f32 v[8:9], v[164:165], v[12:13], v[50:51] op_sel_hi:[1,0,1] neg_lo:[1,0,0] neg_hi:[1,0,0]
	ds_read_b128 v[20:23], v10 offset:41216
	ds_read_b128 v[28:31], v10 offset:41728
	ds_read_b128 v[24:27], v10 offset:41472
	ds_read_b128 v[66:69], v11 offset:2560
	s_waitcnt lgkmcnt(4)
	s_nop 0
	v_fma_mix_f32 v12, v6, v188, v180 op_sel_hi:[0,1,0]
	v_fma_mix_f32 v12, v7, v188, v12 op_sel:[0,1,0] op_sel_hi:[0,1,0]
	v_fma_mix_f32 v12, v8, v189, v12 op_sel_hi:[0,1,0]
	v_fma_mix_f32 v12, v9, v189, v12 op_sel:[0,1,0] op_sel_hi:[0,1,0]
	v_fma_mix_f32 v57, v6, v160, v180 op_sel_hi:[0,1,0]
	v_fma_mix_f32 v57, v7, v160, v57 op_sel:[0,1,0] op_sel_hi:[0,1,0]
	v_add_f32_dpp v12, v12, v12 row_ror:1 row_mask:0xf bank_mask:0xf bound_ctrl:1
	v_fma_mix_f32 v57, v8, v161, v57 op_sel_hi:[0,1,0]
	v_fma_mix_f32 v57, v9, v161, v57 op_sel:[0,1,0] op_sel_hi:[0,1,0]
	v_add_f32_dpp v12, v12, v12 row_ror:2 row_mask:0xf bank_mask:0xf bound_ctrl:1
	v_pk_fma_f32 v[48:49], v[196:197], v[72:73], v[6:7] op_sel_hi:[1,0,1]
	v_pk_fma_f32 v[50:51], v[198:199], v[72:73], v[8:9] op_sel_hi:[1,0,1]
	v_add_f32_dpp v12, v12, v12 row_ror:4 row_mask:0xf bank_mask:0xf bound_ctrl:1
	v_add_f32_dpp v137, v137, v137 row_ror:8 row_mask:0xf bank_mask:0xc
	v_add_f32_dpp v137, v129, v129 row_ror:8 row_mask:0xf bank_mask:0x3
	v_add_f32_dpp v12, v12, v12 row_ror:8 row_mask:0xf bank_mask:0xf bound_ctrl:1
	v_pk_fma_f32 v[6:7], v[192:193], v[12:13], v[48:49] op_sel_hi:[1,0,1] neg_lo:[1,0,0] neg_hi:[1,0,0]
	v_pk_fma_f32 v[8:9], v[194:195], v[12:13], v[50:51] op_sel_hi:[1,0,1] neg_lo:[1,0,0] neg_hi:[1,0,0]
	ds_read_b128 v[36:39], v10 offset:42240
	ds_read_b128 v[44:47], v10 offset:42752
	ds_read_b128 v[40:43], v10 offset:42496
	v_fma_mix_f32 v12, v6, v204, v180 op_sel_hi:[0,1,0]
	v_fma_mix_f32 v12, v7, v204, v12 op_sel:[0,1,0] op_sel_hi:[0,1,0]
	v_fma_mix_f32 v12, v8, v205, v12 op_sel_hi:[0,1,0]
	v_fma_mix_f32 v12, v9, v205, v12 op_sel:[0,1,0] op_sel_hi:[0,1,0]
	v_fma_mix_f32 v81, v6, v190, v180 op_sel_hi:[0,1,0]
	v_fma_mix_f32 v81, v7, v190, v81 op_sel:[0,1,0] op_sel_hi:[0,1,0]
	v_add_f32_dpp v12, v12, v12 row_ror:1 row_mask:0xf bank_mask:0xf bound_ctrl:1
	v_fma_mix_f32 v81, v8, v191, v81 op_sel_hi:[0,1,0]
	v_fma_mix_f32 v81, v9, v191, v81 op_sel:[0,1,0] op_sel_hi:[0,1,0]
	v_add_f32_dpp v12, v12, v12 row_ror:2 row_mask:0xf bank_mask:0xf bound_ctrl:1
	v_pk_fma_f32 v[48:49], v[212:213], v[72:73], v[6:7] op_sel:[0,1,0]
	v_pk_fma_f32 v[50:51], v[214:215], v[72:73], v[8:9] op_sel:[0,1,0]
	v_add_f32_dpp v12, v12, v12 row_ror:4 row_mask:0xf bank_mask:0xf bound_ctrl:1
	v_add_f32_dpp v134, v134, v134 row_ror:4 row_mask:0xf bank_mask:0xa
	v_add_f32_dpp v134, v130, v130 row_ror:12 row_mask:0xf bank_mask:0x5
	v_add_f32_dpp v135, v135, v135 row_ror:4 row_mask:0xf bank_mask:0xa
	v_add_f32_dpp v12, v12, v12 row_ror:8 row_mask:0xf bank_mask:0xf bound_ctrl:1
	v_pk_fma_f32 v[6:7], v[208:209], v[12:13], v[48:49] op_sel_hi:[1,0,1] neg_lo:[1,0,0] neg_hi:[1,0,0]
	v_pk_fma_f32 v[8:9], v[210:211], v[12:13], v[50:51] op_sel_hi:[1,0,1] neg_lo:[1,0,0] neg_hi:[1,0,0]
	v_pk_mul_f32 v[6:7], v[6:7], v[200:201]
	v_pk_mul_f32 v[8:9], v[8:9], v[202:203]
	ds_read_b128 v[88:91], v10 offset:43264
	ds_read_b128 v[96:99], v10 offset:43776
	ds_read_b128 v[92:95], v10 offset:43520
	s_waitcnt lgkmcnt(3)
	s_nop 0
	v_fma_mix_f32 v12, v6, v20, v180 op_sel_hi:[0,1,0]
	v_fma_mix_f32 v12, v7, v20, v12 op_sel:[0,1,0] op_sel_hi:[0,1,0]
	v_fma_mix_f32 v12, v8, v21, v12 op_sel_hi:[0,1,0]
	v_fma_mix_f32 v12, v9, v21, v12 op_sel:[0,1,0] op_sel_hi:[0,1,0]
	v_fma_mix_f32 v82, v6, v206, v180 op_sel_hi:[0,1,0]
	v_fma_mix_f32 v82, v7, v206, v82 op_sel:[0,1,0] op_sel_hi:[0,1,0]
	v_add_f32_dpp v12, v12, v12 row_ror:1 row_mask:0xf bank_mask:0xf bound_ctrl:1
	v_fma_mix_f32 v82, v8, v207, v82 op_sel_hi:[0,1,0]
	v_fma_mix_f32 v82, v9, v207, v82 op_sel:[0,1,0] op_sel_hi:[0,1,0]
	v_add_f32_dpp v12, v12, v12 row_ror:2 row_mask:0xf bank_mask:0xf bound_ctrl:1
	v_pk_fma_f32 v[48:49], v[28:29], v[66:67], v[6:7] op_sel_hi:[1,0,1]
	v_pk_fma_f32 v[50:51], v[30:31], v[66:67], v[8:9] op_sel_hi:[1,0,1]
	v_add_f32_dpp v12, v12, v12 row_ror:4 row_mask:0xf bank_mask:0xf bound_ctrl:1
	v_add_f32_dpp v135, v131, v131 row_ror:12 row_mask:0xf bank_mask:0x5
	v_add_f32_dpp v136, v136, v136 row_ror:4 row_mask:0xf bank_mask:0xa
	v_add_f32_dpp v136, v132, v132 row_ror:12 row_mask:0xf bank_mask:0x5
	v_add_f32_dpp v12, v12, v12 row_ror:8 row_mask:0xf bank_mask:0xf bound_ctrl:1
	v_pk_fma_f32 v[6:7], v[24:25], v[12:13], v[48:49] op_sel_hi:[1,0,1] neg_lo:[1,0,0] neg_hi:[1,0,0]
	v_pk_fma_f32 v[8:9], v[26:27], v[12:13], v[50:51] op_sel_hi:[1,0,1] neg_lo:[1,0,0] neg_hi:[1,0,0]
	ds_read_b128 v[110:113], v10 offset:44288
	ds_read_b128 v[106:109], v10 offset:44032
	ds_read_b128 v[118:121], v10 offset:44800
	ds_read_b128 v[114:117], v10 offset:44544
	v_fma_mix_f32 v12, v6, v36, v180 op_sel_hi:[0,1,0]
	v_fma_mix_f32 v12, v7, v36, v12 op_sel:[0,1,0] op_sel_hi:[0,1,0]
	v_fma_mix_f32 v12, v8, v37, v12 op_sel_hi:[0,1,0]
	v_fma_mix_f32 v12, v9, v37, v12 op_sel:[0,1,0] op_sel_hi:[0,1,0]
	v_fma_mix_f32 v83, v6, v22, v180 op_sel_hi:[0,1,0]
	v_fma_mix_f32 v83, v7, v22, v83 op_sel:[0,1,0] op_sel_hi:[0,1,0]
	v_add_f32_dpp v12, v12, v12 row_ror:1 row_mask:0xf bank_mask:0xf bound_ctrl:1
	v_fma_mix_f32 v83, v8, v23, v83 op_sel_hi:[0,1,0]
	v_fma_mix_f32 v83, v9, v23, v83 op_sel:[0,1,0] op_sel_hi:[0,1,0]
	v_add_f32_dpp v12, v12, v12 row_ror:2 row_mask:0xf bank_mask:0xf bound_ctrl:1
	v_pk_fma_f32 v[48:49], v[44:45], v[66:67], v[6:7] op_sel:[0,1,0]
	v_pk_fma_f32 v[50:51], v[46:47], v[66:67], v[8:9] op_sel:[0,1,0]
	v_add_f32_dpp v12, v12, v12 row_ror:4 row_mask:0xf bank_mask:0xf bound_ctrl:1
	v_add_f32_dpp v137, v137, v137 row_ror:4 row_mask:0xf bank_mask:0xa
	v_add_f32_dpp v137, v133, v133 row_ror:12 row_mask:0xf bank_mask:0x5
	v_add_f32_dpp v12, v12, v12 row_ror:8 row_mask:0xf bank_mask:0xf bound_ctrl:1
	v_pk_fma_f32 v[6:7], v[40:41], v[12:13], v[48:49] op_sel_hi:[1,0,1] neg_lo:[1,0,0] neg_hi:[1,0,0]
	v_pk_fma_f32 v[8:9], v[42:43], v[12:13], v[50:51] op_sel_hi:[1,0,1] neg_lo:[1,0,0] neg_hi:[1,0,0]
	ds_read_b128 v[142:145], v10 offset:45312
	ds_read_b128 v[150:153], v10 offset:45824
	ds_read_b128 v[146:149], v10 offset:45568
	ds_read_b128 v[70:73], v11 offset:2816
	s_waitcnt lgkmcnt(4)
	s_nop 0
	v_fma_mix_f32 v12, v6, v88, v180 op_sel_hi:[0,1,0]
	v_fma_mix_f32 v12, v7, v88, v12 op_sel:[0,1,0] op_sel_hi:[0,1,0]
	v_fma_mix_f32 v12, v8, v89, v12 op_sel_hi:[0,1,0]
	v_fma_mix_f32 v12, v9, v89, v12 op_sel:[0,1,0] op_sel_hi:[0,1,0]
	v_fma_mix_f32 v100, v6, v38, v180 op_sel_hi:[0,1,0]
	v_fma_mix_f32 v100, v7, v38, v100 op_sel:[0,1,0] op_sel_hi:[0,1,0]
	v_add_f32_dpp v12, v12, v12 row_ror:1 row_mask:0xf bank_mask:0xf bound_ctrl:1
	v_fma_mix_f32 v100, v8, v39, v100 op_sel_hi:[0,1,0]
	v_fma_mix_f32 v100, v9, v39, v100 op_sel:[0,1,0] op_sel_hi:[0,1,0]
	v_add_f32_dpp v12, v12, v12 row_ror:2 row_mask:0xf bank_mask:0xf bound_ctrl:1
	v_pk_fma_f32 v[48:49], v[96:97], v[68:69], v[6:7] op_sel_hi:[1,0,1]
	v_pk_fma_f32 v[50:51], v[98:99], v[68:69], v[8:9] op_sel_hi:[1,0,1]
	v_add_f32_dpp v12, v12, v12 row_ror:4 row_mask:0xf bank_mask:0xf bound_ctrl:1
	v_cndmask_b32_e64 v62, v136, v134, s[38:39]
	v_cndmask_b32_e64 v63, v134, v136, s[38:39]
	v_add_f32_dpp v12, v12, v12 row_ror:8 row_mask:0xf bank_mask:0xf bound_ctrl:1
	v_pk_fma_f32 v[6:7], v[92:93], v[12:13], v[48:49] op_sel_hi:[1,0,1] neg_lo:[1,0,0] neg_hi:[1,0,0]
	v_pk_fma_f32 v[8:9], v[94:95], v[12:13], v[50:51] op_sel_hi:[1,0,1] neg_lo:[1,0,0] neg_hi:[1,0,0]
	ds_read_b128 v[158:161], v10 offset:46336
	ds_read_b128 v[166:169], v10 offset:46848
	ds_read_b128 v[162:165], v10 offset:46592
	v_fma_mix_f32 v12, v6, v110, v180 op_sel_hi:[0,1,0]
	v_fma_mix_f32 v12, v7, v110, v12 op_sel:[0,1,0] op_sel_hi:[0,1,0]
	v_fma_mix_f32 v12, v8, v111, v12 op_sel_hi:[0,1,0]
	v_fma_mix_f32 v12, v9, v111, v12 op_sel:[0,1,0] op_sel_hi:[0,1,0]
	v_fma_mix_f32 v101, v6, v90, v180 op_sel_hi:[0,1,0]
	v_fma_mix_f32 v101, v7, v90, v101 op_sel:[0,1,0] op_sel_hi:[0,1,0]
	v_add_f32_dpp v12, v12, v12 row_ror:1 row_mask:0xf bank_mask:0xf bound_ctrl:1
	v_fma_mix_f32 v101, v8, v91, v101 op_sel_hi:[0,1,0]
	v_fma_mix_f32 v101, v9, v91, v101 op_sel:[0,1,0] op_sel_hi:[0,1,0]
	v_add_f32_dpp v12, v12, v12 row_ror:2 row_mask:0xf bank_mask:0xf bound_ctrl:1
	v_pk_fma_f32 v[48:49], v[118:119], v[68:69], v[6:7] op_sel:[0,1,0]
	v_pk_fma_f32 v[50:51], v[120:121], v[68:69], v[8:9] op_sel:[0,1,0]
	v_add_f32_dpp v12, v12, v12 row_ror:4 row_mask:0xf bank_mask:0xf bound_ctrl:1
	v_cndmask_b32_e64 v64, v137, v135, s[38:39]
	v_cndmask_b32_e64 v65, v135, v137, s[38:39]
	v_add_f32_dpp v12, v12, v12 row_ror:8 row_mask:0xf bank_mask:0xf bound_ctrl:1
	v_pk_fma_f32 v[6:7], v[114:115], v[12:13], v[48:49] op_sel_hi:[1,0,1] neg_lo:[1,0,0] neg_hi:[1,0,0]
	v_pk_fma_f32 v[8:9], v[116:117], v[12:13], v[50:51] op_sel_hi:[1,0,1] neg_lo:[1,0,0] neg_hi:[1,0,0]
	v_pk_mul_f32 v[6:7], v[6:7], v[106:107]
	v_pk_mul_f32 v[8:9], v[8:9], v[108:109]
	ds_read_b128 v[188:191], v10 offset:47360
	ds_read_b128 v[196:199], v10 offset:47872
	ds_read_b128 v[192:195], v10 offset:47616
	s_waitcnt lgkmcnt(3)
	s_nop 0
	v_fma_mix_f32 v12, v6, v142, v180 op_sel_hi:[0,1,0]
	v_fma_mix_f32 v12, v7, v142, v12 op_sel:[0,1,0] op_sel_hi:[0,1,0]
	v_fma_mix_f32 v12, v8, v143, v12 op_sel_hi:[0,1,0]
	v_fma_mix_f32 v12, v9, v143, v12 op_sel:[0,1,0] op_sel_hi:[0,1,0]
	v_fma_mix_f32 v102, v6, v112, v180 op_sel_hi:[0,1,0]
	v_fma_mix_f32 v102, v7, v112, v102 op_sel:[0,1,0] op_sel_hi:[0,1,0]
	v_add_f32_dpp v12, v12, v12 row_ror:1 row_mask:0xf bank_mask:0xf bound_ctrl:1
	v_fma_mix_f32 v102, v8, v113, v102 op_sel_hi:[0,1,0]
	v_fma_mix_f32 v102, v9, v113, v102 op_sel:[0,1,0] op_sel_hi:[0,1,0]
	v_add_f32_dpp v12, v12, v12 row_ror:2 row_mask:0xf bank_mask:0xf bound_ctrl:1
	v_pk_fma_f32 v[48:49], v[150:151], v[70:71], v[6:7] op_sel_hi:[1,0,1]
	v_pk_fma_f32 v[50:51], v[152:153], v[70:71], v[8:9] op_sel_hi:[1,0,1]
	v_add_f32_dpp v12, v12, v12 row_ror:4 row_mask:0xf bank_mask:0xf bound_ctrl:1
	v_add_f32_dpp v62, v63, v62 quad_perm:[2,3,0,1] row_mask:0xf bank_mask:0xf bound_ctrl:1
	v_add_f32_dpp v63, v65, v64 quad_perm:[2,3,0,1] row_mask:0xf bank_mask:0xf bound_ctrl:1
	v_add_f32_dpp v12, v12, v12 row_ror:8 row_mask:0xf bank_mask:0xf bound_ctrl:1
	v_pk_fma_f32 v[6:7], v[146:147], v[12:13], v[48:49] op_sel_hi:[1,0,1] neg_lo:[1,0,0] neg_hi:[1,0,0]
	v_pk_fma_f32 v[8:9], v[148:149], v[12:13], v[50:51] op_sel_hi:[1,0,1] neg_lo:[1,0,0] neg_hi:[1,0,0]
	ds_read_b128 v[204:207], v10 offset:48384
	ds_read_b128 v[200:203], v10 offset:48128
	ds_read_b128 v[212:215], v10 offset:48896
	ds_read_b128 v[208:211], v10 offset:48640
	v_fma_mix_f32 v12, v6, v158, v180 op_sel_hi:[0,1,0]
	v_fma_mix_f32 v12, v7, v158, v12 op_sel:[0,1,0] op_sel_hi:[0,1,0]
	v_fma_mix_f32 v12, v8, v159, v12 op_sel_hi:[0,1,0]
	v_fma_mix_f32 v12, v9, v159, v12 op_sel:[0,1,0] op_sel_hi:[0,1,0]
	v_fma_mix_f32 v103, v6, v144, v180 op_sel_hi:[0,1,0]
	v_fma_mix_f32 v103, v7, v144, v103 op_sel:[0,1,0] op_sel_hi:[0,1,0]
	v_add_f32_dpp v12, v12, v12 row_ror:1 row_mask:0xf bank_mask:0xf bound_ctrl:1
	v_fma_mix_f32 v103, v8, v145, v103 op_sel_hi:[0,1,0]
	v_fma_mix_f32 v103, v9, v145, v103 op_sel:[0,1,0] op_sel_hi:[0,1,0]
	v_add_f32_dpp v12, v12, v12 row_ror:2 row_mask:0xf bank_mask:0xf bound_ctrl:1
	v_pk_fma_f32 v[48:49], v[166:167], v[70:71], v[6:7] op_sel:[0,1,0]
	v_pk_fma_f32 v[50:51], v[168:169], v[70:71], v[8:9] op_sel:[0,1,0]
	v_add_f32_dpp v12, v12, v12 row_ror:4 row_mask:0xf bank_mask:0xf bound_ctrl:1
	v_cndmask_b32_e64 v65, v63, v62, s[40:41]
	v_cndmask_b32_e64 v62, v62, v63, s[40:41]
	v_add_f32_dpp v12, v12, v12 row_ror:8 row_mask:0xf bank_mask:0xf bound_ctrl:1
	v_pk_fma_f32 v[6:7], v[162:163], v[12:13], v[48:49] op_sel_hi:[1,0,1] neg_lo:[1,0,0] neg_hi:[1,0,0]
	v_pk_fma_f32 v[8:9], v[164:165], v[12:13], v[50:51] op_sel_hi:[1,0,1] neg_lo:[1,0,0] neg_hi:[1,0,0]
	ds_read_b128 v[20:23], v10 offset:49408
	ds_read_b128 v[28:31], v10 offset:49920
	ds_read_b128 v[24:27], v10 offset:49664
	ds_read_b128 v[66:69], v11 offset:3072
	s_waitcnt lgkmcnt(4)
	s_nop 0
	v_fma_mix_f32 v12, v6, v188, v180 op_sel_hi:[0,1,0]
	v_fma_mix_f32 v12, v7, v188, v12 op_sel:[0,1,0] op_sel_hi:[0,1,0]
	v_fma_mix_f32 v12, v8, v189, v12 op_sel_hi:[0,1,0]
	v_fma_mix_f32 v12, v9, v189, v12 op_sel:[0,1,0] op_sel_hi:[0,1,0]
	v_fma_mix_f32 v104, v6, v160, v180 op_sel_hi:[0,1,0]
	v_fma_mix_f32 v104, v7, v160, v104 op_sel:[0,1,0] op_sel_hi:[0,1,0]
	v_add_f32_dpp v12, v12, v12 row_ror:1 row_mask:0xf bank_mask:0xf bound_ctrl:1
	v_fma_mix_f32 v104, v8, v161, v104 op_sel_hi:[0,1,0]
	v_fma_mix_f32 v104, v9, v161, v104 op_sel:[0,1,0] op_sel_hi:[0,1,0]
	v_add_f32_dpp v12, v12, v12 row_ror:2 row_mask:0xf bank_mask:0xf bound_ctrl:1
	v_pk_fma_f32 v[48:49], v[196:197], v[72:73], v[6:7] op_sel_hi:[1,0,1]
	v_pk_fma_f32 v[50:51], v[198:199], v[72:73], v[8:9] op_sel_hi:[1,0,1]
	v_add_f32_dpp v12, v12, v12 row_ror:4 row_mask:0xf bank_mask:0xf bound_ctrl:1
	v_add_f32_dpp v62, v62, v65 quad_perm:[1,0,3,2] row_mask:0xf bank_mask:0xf bound_ctrl:1
	v_cvt_pk_bf16_f32 v62, v62, v62
	v_add_f32_dpp v12, v12, v12 row_ror:8 row_mask:0xf bank_mask:0xf bound_ctrl:1
	v_pk_fma_f32 v[6:7], v[192:193], v[12:13], v[48:49] op_sel_hi:[1,0,1] neg_lo:[1,0,0] neg_hi:[1,0,0]
	v_pk_fma_f32 v[8:9], v[194:195], v[12:13], v[50:51] op_sel_hi:[1,0,1] neg_lo:[1,0,0] neg_hi:[1,0,0]
	ds_read_b128 v[36:39], v10 offset:50432
	ds_read_b128 v[44:47], v10 offset:50944
	ds_read_b128 v[40:43], v10 offset:50688
	v_fma_mix_f32 v12, v6, v204, v180 op_sel_hi:[0,1,0]
	v_fma_mix_f32 v12, v7, v204, v12 op_sel:[0,1,0] op_sel_hi:[0,1,0]
	v_fma_mix_f32 v12, v8, v205, v12 op_sel_hi:[0,1,0]
	v_fma_mix_f32 v12, v9, v205, v12 op_sel:[0,1,0] op_sel_hi:[0,1,0]
	v_fma_mix_f32 v105, v6, v190, v180 op_sel_hi:[0,1,0]
	v_fma_mix_f32 v105, v7, v190, v105 op_sel:[0,1,0] op_sel_hi:[0,1,0]
	v_add_f32_dpp v12, v12, v12 row_ror:1 row_mask:0xf bank_mask:0xf bound_ctrl:1
	v_fma_mix_f32 v105, v8, v191, v105 op_sel_hi:[0,1,0]
	v_fma_mix_f32 v105, v9, v191, v105 op_sel:[0,1,0] op_sel_hi:[0,1,0]
	v_add_f32_dpp v12, v12, v12 row_ror:2 row_mask:0xf bank_mask:0xf bound_ctrl:1
	v_pk_fma_f32 v[48:49], v[212:213], v[72:73], v[6:7] op_sel:[0,1,0]
	v_pk_fma_f32 v[50:51], v[214:215], v[72:73], v[8:9] op_sel:[0,1,0]
	v_add_f32_dpp v12, v12, v12 row_ror:4 row_mask:0xf bank_mask:0xf bound_ctrl:1
	global_store_short v[2:3], v62, off
	v_lshl_add_u64 v[2:3], v[2:3], 0, s[84:85]
	v_add_f32_dpp v12, v12, v12 row_ror:8 row_mask:0xf bank_mask:0xf bound_ctrl:1
	v_pk_fma_f32 v[6:7], v[208:209], v[12:13], v[48:49] op_sel_hi:[1,0,1] neg_lo:[1,0,0] neg_hi:[1,0,0]
	v_pk_fma_f32 v[8:9], v[210:211], v[12:13], v[50:51] op_sel_hi:[1,0,1] neg_lo:[1,0,0] neg_hi:[1,0,0]
	v_pk_mul_f32 v[6:7], v[6:7], v[200:201]
	v_pk_mul_f32 v[8:9], v[8:9], v[202:203]
	ds_read_b128 v[88:91], v10 offset:51456
	ds_read_b128 v[96:99], v10 offset:51968
	ds_read_b128 v[92:95], v10 offset:51712
	s_waitcnt lgkmcnt(3)
	s_nop 0
	v_fma_mix_f32 v12, v6, v20, v180 op_sel_hi:[0,1,0]
	v_fma_mix_f32 v12, v7, v20, v12 op_sel:[0,1,0] op_sel_hi:[0,1,0]
	v_fma_mix_f32 v12, v8, v21, v12 op_sel_hi:[0,1,0]
	v_fma_mix_f32 v12, v9, v21, v12 op_sel:[0,1,0] op_sel_hi:[0,1,0]
	v_fma_mix_f32 v61, v6, v206, v180 op_sel_hi:[0,1,0]
	v_fma_mix_f32 v61, v7, v206, v61 op_sel:[0,1,0] op_sel_hi:[0,1,0]
	v_add_f32_dpp v12, v12, v12 row_ror:1 row_mask:0xf bank_mask:0xf bound_ctrl:1
	v_fma_mix_f32 v61, v8, v207, v61 op_sel_hi:[0,1,0]
	v_fma_mix_f32 v61, v9, v207, v61 op_sel:[0,1,0] op_sel_hi:[0,1,0]
	v_add_f32_dpp v12, v12, v12 row_ror:2 row_mask:0xf bank_mask:0xf bound_ctrl:1
	v_pk_fma_f32 v[48:49], v[28:29], v[66:67], v[6:7] op_sel_hi:[1,0,1]
	v_pk_fma_f32 v[50:51], v[30:31], v[66:67], v[8:9] op_sel_hi:[1,0,1]
	v_add_f32_dpp v12, v12, v12 row_ror:4 row_mask:0xf bank_mask:0xf bound_ctrl:1
	s_nop 1
	s_nop 0
	v_add_f32_dpp v12, v12, v12 row_ror:8 row_mask:0xf bank_mask:0xf bound_ctrl:1
	v_pk_fma_f32 v[6:7], v[24:25], v[12:13], v[48:49] op_sel_hi:[1,0,1] neg_lo:[1,0,0] neg_hi:[1,0,0]
	v_pk_fma_f32 v[8:9], v[26:27], v[12:13], v[50:51] op_sel_hi:[1,0,1] neg_lo:[1,0,0] neg_hi:[1,0,0]
	ds_read_b128 v[110:113], v10 offset:52480
	ds_read_b128 v[106:109], v10 offset:52224
	ds_read_b128 v[118:121], v10 offset:52992
	ds_read_b128 v[114:117], v10 offset:52736
	v_fma_mix_f32 v12, v6, v36, v180 op_sel_hi:[0,1,0]
	v_fma_mix_f32 v12, v7, v36, v12 op_sel:[0,1,0] op_sel_hi:[0,1,0]
	v_fma_mix_f32 v12, v8, v37, v12 op_sel_hi:[0,1,0]
	v_fma_mix_f32 v12, v9, v37, v12 op_sel:[0,1,0] op_sel_hi:[0,1,0]
	v_fma_mix_f32 v122, v6, v22, v180 op_sel_hi:[0,1,0]
	v_fma_mix_f32 v122, v7, v22, v122 op_sel:[0,1,0] op_sel_hi:[0,1,0]
	v_add_f32_dpp v12, v12, v12 row_ror:1 row_mask:0xf bank_mask:0xf bound_ctrl:1
	v_fma_mix_f32 v122, v8, v23, v122 op_sel_hi:[0,1,0]
	v_fma_mix_f32 v122, v9, v23, v122 op_sel:[0,1,0] op_sel_hi:[0,1,0]
	v_add_f32_dpp v12, v12, v12 row_ror:2 row_mask:0xf bank_mask:0xf bound_ctrl:1
	v_pk_fma_f32 v[48:49], v[44:45], v[66:67], v[6:7] op_sel:[0,1,0]
	v_pk_fma_f32 v[50:51], v[46:47], v[66:67], v[8:9] op_sel:[0,1,0]
	v_add_f32_dpp v12, v12, v12 row_ror:4 row_mask:0xf bank_mask:0xf bound_ctrl:1
	v_add_f32_dpp v83, v83, v83 row_ror:8 row_mask:0xf bank_mask:0xc
	v_add_f32_dpp v83, v52, v52 row_ror:8 row_mask:0xf bank_mask:0x3
	v_add_f32_dpp v100, v100, v100 row_ror:8 row_mask:0xf bank_mask:0xc
	v_add_f32_dpp v12, v12, v12 row_ror:8 row_mask:0xf bank_mask:0xf bound_ctrl:1
	v_pk_fma_f32 v[6:7], v[40:41], v[12:13], v[48:49] op_sel_hi:[1,0,1] neg_lo:[1,0,0] neg_hi:[1,0,0]
	v_pk_fma_f32 v[8:9], v[42:43], v[12:13], v[50:51] op_sel_hi:[1,0,1] neg_lo:[1,0,0] neg_hi:[1,0,0]
	ds_read_b128 v[142:145], v10 offset:53504
	ds_read_b128 v[150:153], v10 offset:54016
	ds_read_b128 v[146:149], v10 offset:53760
	ds_read_b128 v[70:73], v11 offset:3328
	s_waitcnt lgkmcnt(4)
	s_nop 0
	v_fma_mix_f32 v12, v6, v88, v180 op_sel_hi:[0,1,0]
	v_fma_mix_f32 v12, v7, v88, v12 op_sel:[0,1,0] op_sel_hi:[0,1,0]
	v_fma_mix_f32 v12, v8, v89, v12 op_sel_hi:[0,1,0]
	v_fma_mix_f32 v12, v9, v89, v12 op_sel:[0,1,0] op_sel_hi:[0,1,0]
	v_fma_mix_f32 v123, v6, v38, v180 op_sel_hi:[0,1,0]
	v_fma_mix_f32 v123, v7, v38, v123 op_sel:[0,1,0] op_sel_hi:[0,1,0]
	v_add_f32_dpp v12, v12, v12 row_ror:1 row_mask:0xf bank_mask:0xf bound_ctrl:1
	v_fma_mix_f32 v123, v8, v39, v123 op_sel_hi:[0,1,0]
	v_fma_mix_f32 v123, v9, v39, v123 op_sel:[0,1,0] op_sel_hi:[0,1,0]
	v_add_f32_dpp v12, v12, v12 row_ror:2 row_mask:0xf bank_mask:0xf bound_ctrl:1
	v_pk_fma_f32 v[48:49], v[96:97], v[68:69], v[6:7] op_sel_hi:[1,0,1]
	v_pk_fma_f32 v[50:51], v[98:99], v[68:69], v[8:9] op_sel_hi:[1,0,1]
	v_add_f32_dpp v12, v12, v12 row_ror:4 row_mask:0xf bank_mask:0xf bound_ctrl:1
	v_add_f32_dpp v100, v53, v53 row_ror:8 row_mask:0xf bank_mask:0x3
	v_add_f32_dpp v101, v101, v101 row_ror:8 row_mask:0xf bank_mask:0xc
	v_add_f32_dpp v101, v54, v54 row_ror:8 row_mask:0xf bank_mask:0x3
	v_add_f32_dpp v12, v12, v12 row_ror:8 row_mask:0xf bank_mask:0xf bound_ctrl:1
	v_pk_fma_f32 v[6:7], v[92:93], v[12:13], v[48:49] op_sel_hi:[1,0,1] neg_lo:[1,0,0] neg_hi:[1,0,0]
	v_pk_fma_f32 v[8:9], v[94:95], v[12:13], v[50:51] op_sel_hi:[1,0,1] neg_lo:[1,0,0] neg_hi:[1,0,0]
	ds_read_b128 v[158:161], v10 offset:54528
	ds_read_b128 v[166:169], v10 offset:55040
	ds_read_b128 v[162:165], v10 offset:54784
	v_fma_mix_f32 v12, v6, v110, v180 op_sel_hi:[0,1,0]
	v_fma_mix_f32 v12, v7, v110, v12 op_sel:[0,1,0] op_sel_hi:[0,1,0]
	v_fma_mix_f32 v12, v8, v111, v12 op_sel_hi:[0,1,0]
	v_fma_mix_f32 v12, v9, v111, v12 op_sel:[0,1,0] op_sel_hi:[0,1,0]
	v_fma_mix_f32 v124, v6, v90, v180 op_sel_hi:[0,1,0]
	v_fma_mix_f32 v124, v7, v90, v124 op_sel:[0,1,0] op_sel_hi:[0,1,0]
	v_add_f32_dpp v12, v12, v12 row_ror:1 row_mask:0xf bank_mask:0xf bound_ctrl:1
	v_fma_mix_f32 v124, v8, v91, v124 op_sel_hi:[0,1,0]
	v_fma_mix_f32 v124, v9, v91, v124 op_sel:[0,1,0] op_sel_hi:[0,1,0]
	v_add_f32_dpp v12, v12, v12 row_ror:2 row_mask:0xf bank_mask:0xf bound_ctrl:1
	v_pk_fma_f32 v[48:49], v[118:119], v[68:69], v[6:7] op_sel:[0,1,0]
	v_pk_fma_f32 v[50:51], v[120:121], v[68:69], v[8:9] op_sel:[0,1,0]
	v_add_f32_dpp v12, v12, v12 row_ror:4 row_mask:0xf bank_mask:0xf bound_ctrl:1
	v_add_f32_dpp v102, v102, v102 row_ror:8 row_mask:0xf bank_mask:0xc
	v_add_f32_dpp v102, v55, v55 row_ror:8 row_mask:0xf bank_mask:0x3
	v_add_f32_dpp v103, v103, v103 row_ror:8 row_mask:0xf bank_mask:0xc
	v_add_f32_dpp v12, v12, v12 row_ror:8 row_mask:0xf bank_mask:0xf bound_ctrl:1
	v_pk_fma_f32 v[6:7], v[114:115], v[12:13], v[48:49] op_sel_hi:[1,0,1] neg_lo:[1,0,0] neg_hi:[1,0,0]
	v_pk_fma_f32 v[8:9], v[116:117], v[12:13], v[50:51] op_sel_hi:[1,0,1] neg_lo:[1,0,0] neg_hi:[1,0,0]
	v_pk_mul_f32 v[6:7], v[6:7], v[106:107]
	v_pk_mul_f32 v[8:9], v[8:9], v[108:109]
	ds_read_b128 v[188:191], v10 offset:55552
	ds_read_b128 v[196:199], v10 offset:56064
	ds_read_b128 v[192:195], v10 offset:55808
	s_waitcnt lgkmcnt(3)
	s_nop 0
	v_fma_mix_f32 v12, v6, v142, v180 op_sel_hi:[0,1,0]
	v_fma_mix_f32 v12, v7, v142, v12 op_sel:[0,1,0] op_sel_hi:[0,1,0]
	v_fma_mix_f32 v12, v8, v143, v12 op_sel_hi:[0,1,0]
	v_fma_mix_f32 v12, v9, v143, v12 op_sel:[0,1,0] op_sel_hi:[0,1,0]
	v_fma_mix_f32 v125, v6, v112, v180 op_sel_hi:[0,1,0]
	v_fma_mix_f32 v125, v7, v112, v125 op_sel:[0,1,0] op_sel_hi:[0,1,0]
	v_add_f32_dpp v12, v12, v12 row_ror:1 row_mask:0xf bank_mask:0xf bound_ctrl:1
	v_fma_mix_f32 v125, v8, v113, v125 op_sel_hi:[0,1,0]
	v_fma_mix_f32 v125, v9, v113, v125 op_sel:[0,1,0] op_sel_hi:[0,1,0]
	v_add_f32_dpp v12, v12, v12 row_ror:2 row_mask:0xf bank_mask:0xf bound_ctrl:1
	v_pk_fma_f32 v[48:49], v[150:151], v[70:71], v[6:7] op_sel_hi:[1,0,1]
	v_pk_fma_f32 v[50:51], v[152:153], v[70:71], v[8:9] op_sel_hi:[1,0,1]
	v_add_f32_dpp v12, v12, v12 row_ror:4 row_mask:0xf bank_mask:0xf bound_ctrl:1
	v_add_f32_dpp v103, v56, v56 row_ror:8 row_mask:0xf bank_mask:0x3
	v_add_f32_dpp v104, v104, v104 row_ror:8 row_mask:0xf bank_mask:0xc
	v_add_f32_dpp v104, v57, v57 row_ror:8 row_mask:0xf bank_mask:0x3
	v_add_f32_dpp v12, v12, v12 row_ror:8 row_mask:0xf bank_mask:0xf bound_ctrl:1
	v_pk_fma_f32 v[6:7], v[146:147], v[12:13], v[48:49] op_sel_hi:[1,0,1] neg_lo:[1,0,0] neg_hi:[1,0,0]
	v_pk_fma_f32 v[8:9], v[148:149], v[12:13], v[50:51] op_sel_hi:[1,0,1] neg_lo:[1,0,0] neg_hi:[1,0,0]
	ds_read_b128 v[204:207], v10 offset:56576
	ds_read_b128 v[200:203], v10 offset:56320
	ds_read_b128 v[212:215], v10 offset:57088
	ds_read_b128 v[208:211], v10 offset:56832
	v_fma_mix_f32 v12, v6, v158, v180 op_sel_hi:[0,1,0]
	v_fma_mix_f32 v12, v7, v158, v12 op_sel:[0,1,0] op_sel_hi:[0,1,0]
	v_fma_mix_f32 v12, v8, v159, v12 op_sel_hi:[0,1,0]
	v_fma_mix_f32 v12, v9, v159, v12 op_sel:[0,1,0] op_sel_hi:[0,1,0]
	v_fma_mix_f32 v126, v6, v144, v180 op_sel_hi:[0,1,0]
	v_fma_mix_f32 v126, v7, v144, v126 op_sel:[0,1,0] op_sel_hi:[0,1,0]
	v_add_f32_dpp v12, v12, v12 row_ror:1 row_mask:0xf bank_mask:0xf bound_ctrl:1
	v_fma_mix_f32 v126, v8, v145, v126 op_sel_hi:[0,1,0]
	v_fma_mix_f32 v126, v9, v145, v126 op_sel:[0,1,0] op_sel_hi:[0,1,0]
	v_add_f32_dpp v12, v12, v12 row_ror:2 row_mask:0xf bank_mask:0xf bound_ctrl:1
	v_pk_fma_f32 v[48:49], v[166:167], v[70:71], v[6:7] op_sel:[0,1,0]
	v_pk_fma_f32 v[50:51], v[168:169], v[70:71], v[8:9] op_sel:[0,1,0]
	v_add_f32_dpp v12, v12, v12 row_ror:4 row_mask:0xf bank_mask:0xf bound_ctrl:1
	v_add_f32_dpp v105, v105, v105 row_ror:8 row_mask:0xf bank_mask:0xc
	v_add_f32_dpp v105, v81, v81 row_ror:8 row_mask:0xf bank_mask:0x3
	v_add_f32_dpp v12, v12, v12 row_ror:8 row_mask:0xf bank_mask:0xf bound_ctrl:1
	v_pk_fma_f32 v[6:7], v[162:163], v[12:13], v[48:49] op_sel_hi:[1,0,1] neg_lo:[1,0,0] neg_hi:[1,0,0]
	v_pk_fma_f32 v[8:9], v[164:165], v[12:13], v[50:51] op_sel_hi:[1,0,1] neg_lo:[1,0,0] neg_hi:[1,0,0]
	ds_read_b128 v[20:23], v10 offset:57600
	ds_read_b128 v[28:31], v10 offset:58112
	ds_read_b128 v[24:27], v10 offset:57856
	ds_read_b128 v[66:69], v11 offset:3584
	s_waitcnt lgkmcnt(4)
	s_nop 0
	v_fma_mix_f32 v12, v6, v188, v180 op_sel_hi:[0,1,0]
	v_fma_mix_f32 v12, v7, v188, v12 op_sel:[0,1,0] op_sel_hi:[0,1,0]
	v_fma_mix_f32 v12, v8, v189, v12 op_sel_hi:[0,1,0]
	v_fma_mix_f32 v12, v9, v189, v12 op_sel:[0,1,0] op_sel_hi:[0,1,0]
	v_fma_mix_f32 v127, v6, v160, v180 op_sel_hi:[0,1,0]
	v_fma_mix_f32 v127, v7, v160, v127 op_sel:[0,1,0] op_sel_hi:[0,1,0]
	v_add_f32_dpp v12, v12, v12 row_ror:1 row_mask:0xf bank_mask:0xf bound_ctrl:1
	v_fma_mix_f32 v127, v8, v161, v127 op_sel_hi:[0,1,0]
	v_fma_mix_f32 v127, v9, v161, v127 op_sel:[0,1,0] op_sel_hi:[0,1,0]
	v_add_f32_dpp v12, v12, v12 row_ror:2 row_mask:0xf bank_mask:0xf bound_ctrl:1
	v_pk_fma_f32 v[48:49], v[196:197], v[72:73], v[6:7] op_sel_hi:[1,0,1]
	v_pk_fma_f32 v[50:51], v[198:199], v[72:73], v[8:9] op_sel_hi:[1,0,1]
	v_add_f32_dpp v12, v12, v12 row_ror:4 row_mask:0xf bank_mask:0xf bound_ctrl:1
	v_add_f32_dpp v61, v61, v61 row_ror:8 row_mask:0xf bank_mask:0xc
	v_add_f32_dpp v61, v82, v82 row_ror:8 row_mask:0xf bank_mask:0x3
	v_add_f32_dpp v12, v12, v12 row_ror:8 row_mask:0xf bank_mask:0xf bound_ctrl:1
	v_pk_fma_f32 v[6:7], v[192:193], v[12:13], v[48:49] op_sel_hi:[1,0,1] neg_lo:[1,0,0] neg_hi:[1,0,0]
	v_pk_fma_f32 v[8:9], v[194:195], v[12:13], v[50:51] op_sel_hi:[1,0,1] neg_lo:[1,0,0] neg_hi:[1,0,0]
	ds_read_b128 v[36:39], v10 offset:58624
	ds_read_b128 v[44:47], v10 offset:59136
	ds_read_b128 v[40:43], v10 offset:58880
	v_fma_mix_f32 v12, v6, v204, v180 op_sel_hi:[0,1,0]
	v_fma_mix_f32 v12, v7, v204, v12 op_sel:[0,1,0] op_sel_hi:[0,1,0]
	v_fma_mix_f32 v12, v8, v205, v12 op_sel_hi:[0,1,0]
	v_fma_mix_f32 v12, v9, v205, v12 op_sel:[0,1,0] op_sel_hi:[0,1,0]
	v_fma_mix_f32 v128, v6, v190, v180 op_sel_hi:[0,1,0]
	v_fma_mix_f32 v128, v7, v190, v128 op_sel:[0,1,0] op_sel_hi:[0,1,0]
	v_add_f32_dpp v12, v12, v12 row_ror:1 row_mask:0xf bank_mask:0xf bound_ctrl:1
	v_fma_mix_f32 v128, v8, v191, v128 op_sel_hi:[0,1,0]
	v_fma_mix_f32 v128, v9, v191, v128 op_sel:[0,1,0] op_sel_hi:[0,1,0]
	v_add_f32_dpp v12, v12, v12 row_ror:2 row_mask:0xf bank_mask:0xf bound_ctrl:1
	v_pk_fma_f32 v[48:49], v[212:213], v[72:73], v[6:7] op_sel:[0,1,0]
	v_pk_fma_f32 v[50:51], v[214:215], v[72:73], v[8:9] op_sel:[0,1,0]
	v_add_f32_dpp v12, v12, v12 row_ror:4 row_mask:0xf bank_mask:0xf bound_ctrl:1
	v_add_f32_dpp v103, v103, v103 row_ror:4 row_mask:0xf bank_mask:0xa
	v_add_f32_dpp v103, v83, v83 row_ror:12 row_mask:0xf bank_mask:0x5
	v_add_f32_dpp v104, v104, v104 row_ror:4 row_mask:0xf bank_mask:0xa
	v_add_f32_dpp v12, v12, v12 row_ror:8 row_mask:0xf bank_mask:0xf bound_ctrl:1
	v_pk_fma_f32 v[6:7], v[208:209], v[12:13], v[48:49] op_sel_hi:[1,0,1] neg_lo:[1,0,0] neg_hi:[1,0,0]
	v_pk_fma_f32 v[8:9], v[210:211], v[12:13], v[50:51] op_sel_hi:[1,0,1] neg_lo:[1,0,0] neg_hi:[1,0,0]
	v_pk_mul_f32 v[6:7], v[6:7], v[200:201]
	v_pk_mul_f32 v[8:9], v[8:9], v[202:203]
	ds_read_b128 v[88:91], v10 offset:59648
	ds_read_b128 v[96:99], v10 offset:60160
	ds_read_b128 v[92:95], v10 offset:59904
	s_waitcnt lgkmcnt(3)
	s_nop 0
	v_fma_mix_f32 v12, v6, v20, v180 op_sel_hi:[0,1,0]
	v_fma_mix_f32 v12, v7, v20, v12 op_sel:[0,1,0] op_sel_hi:[0,1,0]
	v_fma_mix_f32 v12, v8, v21, v12 op_sel_hi:[0,1,0]
	v_fma_mix_f32 v12, v9, v21, v12 op_sel:[0,1,0] op_sel_hi:[0,1,0]
	v_fma_mix_f32 v129, v6, v206, v180 op_sel_hi:[0,1,0]
	v_fma_mix_f32 v129, v7, v206, v129 op_sel:[0,1,0] op_sel_hi:[0,1,0]
	v_add_f32_dpp v12, v12, v12 row_ror:1 row_mask:0xf bank_mask:0xf bound_ctrl:1
	v_fma_mix_f32 v129, v8, v207, v129 op_sel_hi:[0,1,0]
	v_fma_mix_f32 v129, v9, v207, v129 op_sel:[0,1,0] op_sel_hi:[0,1,0]
	v_add_f32_dpp v12, v12, v12 row_ror:2 row_mask:0xf bank_mask:0xf bound_ctrl:1
	v_pk_fma_f32 v[48:49], v[28:29], v[66:67], v[6:7] op_sel_hi:[1,0,1]
	v_pk_fma_f32 v[50:51], v[30:31], v[66:67], v[8:9] op_sel_hi:[1,0,1]
	v_add_f32_dpp v12, v12, v12 row_ror:4 row_mask:0xf bank_mask:0xf bound_ctrl:1
	v_add_f32_dpp v104, v100, v100 row_ror:12 row_mask:0xf bank_mask:0x5
	v_add_f32_dpp v105, v105, v105 row_ror:4 row_mask:0xf bank_mask:0xa
	v_add_f32_dpp v105, v101, v101 row_ror:12 row_mask:0xf bank_mask:0x5
	v_add_f32_dpp v12, v12, v12 row_ror:8 row_mask:0xf bank_mask:0xf bound_ctrl:1
	v_pk_fma_f32 v[6:7], v[24:25], v[12:13], v[48:49] op_sel_hi:[1,0,1] neg_lo:[1,0,0] neg_hi:[1,0,0]
	v_pk_fma_f32 v[8:9], v[26:27], v[12:13], v[50:51] op_sel_hi:[1,0,1] neg_lo:[1,0,0] neg_hi:[1,0,0]
	ds_read_b128 v[110:113], v10 offset:60672
	ds_read_b128 v[106:109], v10 offset:60416
	ds_read_b128 v[118:121], v10 offset:61184
	ds_read_b128 v[114:117], v10 offset:60928
	v_fma_mix_f32 v12, v6, v36, v180 op_sel_hi:[0,1,0]
	v_fma_mix_f32 v12, v7, v36, v12 op_sel:[0,1,0] op_sel_hi:[0,1,0]
	v_fma_mix_f32 v12, v8, v37, v12 op_sel_hi:[0,1,0]
	v_fma_mix_f32 v12, v9, v37, v12 op_sel:[0,1,0] op_sel_hi:[0,1,0]
	v_fma_mix_f32 v130, v6, v22, v180 op_sel_hi:[0,1,0]
	v_fma_mix_f32 v130, v7, v22, v130 op_sel:[0,1,0] op_sel_hi:[0,1,0]
	v_add_f32_dpp v12, v12, v12 row_ror:1 row_mask:0xf bank_mask:0xf bound_ctrl:1
	v_fma_mix_f32 v130, v8, v23, v130 op_sel_hi:[0,1,0]
	v_fma_mix_f32 v130, v9, v23, v130 op_sel:[0,1,0] op_sel_hi:[0,1,0]
	v_add_f32_dpp v12, v12, v12 row_ror:2 row_mask:0xf bank_mask:0xf bound_ctrl:1
	v_pk_fma_f32 v[48:49], v[44:45], v[66:67], v[6:7] op_sel:[0,1,0]
	v_pk_fma_f32 v[50:51], v[46:47], v[66:67], v[8:9] op_sel:[0,1,0]
	v_add_f32_dpp v12, v12, v12 row_ror:4 row_mask:0xf bank_mask:0xf bound_ctrl:1
	v_add_f32_dpp v61, v61, v61 row_ror:4 row_mask:0xf bank_mask:0xa
	v_add_f32_dpp v61, v102, v102 row_ror:12 row_mask:0xf bank_mask:0x5
	v_add_f32_dpp v12, v12, v12 row_ror:8 row_mask:0xf bank_mask:0xf bound_ctrl:1
	v_pk_fma_f32 v[6:7], v[40:41], v[12:13], v[48:49] op_sel_hi:[1,0,1] neg_lo:[1,0,0] neg_hi:[1,0,0]
	v_pk_fma_f32 v[8:9], v[42:43], v[12:13], v[50:51] op_sel_hi:[1,0,1] neg_lo:[1,0,0] neg_hi:[1,0,0]
	ds_read_b128 v[142:145], v10 offset:61696
	ds_read_b128 v[150:153], v10 offset:62208
	ds_read_b128 v[146:149], v10 offset:61952
	ds_read_b128 v[70:73], v11 offset:3840
	s_waitcnt lgkmcnt(4)
	s_nop 0
	v_fma_mix_f32 v12, v6, v88, v180 op_sel_hi:[0,1,0]
	v_fma_mix_f32 v12, v7, v88, v12 op_sel:[0,1,0] op_sel_hi:[0,1,0]
	v_fma_mix_f32 v12, v8, v89, v12 op_sel_hi:[0,1,0]
	v_fma_mix_f32 v12, v9, v89, v12 op_sel:[0,1,0] op_sel_hi:[0,1,0]
	v_fma_mix_f32 v131, v6, v38, v180 op_sel_hi:[0,1,0]
	v_fma_mix_f32 v131, v7, v38, v131 op_sel:[0,1,0] op_sel_hi:[0,1,0]
	v_add_f32_dpp v12, v12, v12 row_ror:1 row_mask:0xf bank_mask:0xf bound_ctrl:1
	v_fma_mix_f32 v131, v8, v39, v131 op_sel_hi:[0,1,0]
	v_fma_mix_f32 v131, v9, v39, v131 op_sel:[0,1,0] op_sel_hi:[0,1,0]
	v_add_f32_dpp v12, v12, v12 row_ror:2 row_mask:0xf bank_mask:0xf bound_ctrl:1
	v_pk_fma_f32 v[48:49], v[96:97], v[68:69], v[6:7] op_sel_hi:[1,0,1]
	v_pk_fma_f32 v[50:51], v[98:99], v[68:69], v[8:9] op_sel_hi:[1,0,1]
	v_add_f32_dpp v12, v12, v12 row_ror:4 row_mask:0xf bank_mask:0xf bound_ctrl:1
	v_cndmask_b32_e64 v62, v105, v103, s[38:39]
	v_cndmask_b32_e64 v63, v103, v105, s[38:39]
	v_add_f32_dpp v12, v12, v12 row_ror:8 row_mask:0xf bank_mask:0xf bound_ctrl:1
	v_pk_fma_f32 v[6:7], v[92:93], v[12:13], v[48:49] op_sel_hi:[1,0,1] neg_lo:[1,0,0] neg_hi:[1,0,0]
	v_pk_fma_f32 v[8:9], v[94:95], v[12:13], v[50:51] op_sel_hi:[1,0,1] neg_lo:[1,0,0] neg_hi:[1,0,0]
	ds_read_b128 v[158:161], v10 offset:62720
	ds_read_b128 v[166:169], v10 offset:63232
	ds_read_b128 v[162:165], v10 offset:62976
	v_fma_mix_f32 v12, v6, v110, v180 op_sel_hi:[0,1,0]
	v_fma_mix_f32 v12, v7, v110, v12 op_sel:[0,1,0] op_sel_hi:[0,1,0]
	v_fma_mix_f32 v12, v8, v111, v12 op_sel_hi:[0,1,0]
	v_fma_mix_f32 v12, v9, v111, v12 op_sel:[0,1,0] op_sel_hi:[0,1,0]
	v_fma_mix_f32 v132, v6, v90, v180 op_sel_hi:[0,1,0]
	v_fma_mix_f32 v132, v7, v90, v132 op_sel:[0,1,0] op_sel_hi:[0,1,0]
	v_add_f32_dpp v12, v12, v12 row_ror:1 row_mask:0xf bank_mask:0xf bound_ctrl:1
	v_fma_mix_f32 v132, v8, v91, v132 op_sel_hi:[0,1,0]
	v_fma_mix_f32 v132, v9, v91, v132 op_sel:[0,1,0] op_sel_hi:[0,1,0]
	v_add_f32_dpp v12, v12, v12 row_ror:2 row_mask:0xf bank_mask:0xf bound_ctrl:1
	v_pk_fma_f32 v[48:49], v[118:119], v[68:69], v[6:7] op_sel:[0,1,0]
	v_pk_fma_f32 v[50:51], v[120:121], v[68:69], v[8:9] op_sel:[0,1,0]
	v_add_f32_dpp v12, v12, v12 row_ror:4 row_mask:0xf bank_mask:0xf bound_ctrl:1
	v_cndmask_b32_e64 v64, v61, v104, s[38:39]
	v_cndmask_b32_e64 v65, v104, v61, s[38:39]
	v_add_f32_dpp v12, v12, v12 row_ror:8 row_mask:0xf bank_mask:0xf bound_ctrl:1
	v_pk_fma_f32 v[6:7], v[114:115], v[12:13], v[48:49] op_sel_hi:[1,0,1] neg_lo:[1,0,0] neg_hi:[1,0,0]
	v_pk_fma_f32 v[8:9], v[116:117], v[12:13], v[50:51] op_sel_hi:[1,0,1] neg_lo:[1,0,0] neg_hi:[1,0,0]
	v_pk_mul_f32 v[6:7], v[6:7], v[106:107]
	v_pk_mul_f32 v[8:9], v[8:9], v[108:109]
	ds_read_b128 v[188:191], v10 offset:63744
	ds_read_b128 v[196:199], v10 offset:64256
	ds_read_b128 v[192:195], v10 offset:64000
	s_waitcnt lgkmcnt(3)
	s_nop 0
	v_fma_mix_f32 v12, v6, v142, v180 op_sel_hi:[0,1,0]
	v_fma_mix_f32 v12, v7, v142, v12 op_sel:[0,1,0] op_sel_hi:[0,1,0]
	v_fma_mix_f32 v12, v8, v143, v12 op_sel_hi:[0,1,0]
	v_fma_mix_f32 v12, v9, v143, v12 op_sel:[0,1,0] op_sel_hi:[0,1,0]
	v_fma_mix_f32 v133, v6, v112, v180 op_sel_hi:[0,1,0]
	v_fma_mix_f32 v133, v7, v112, v133 op_sel:[0,1,0] op_sel_hi:[0,1,0]
	v_add_f32_dpp v12, v12, v12 row_ror:1 row_mask:0xf bank_mask:0xf bound_ctrl:1
	v_fma_mix_f32 v133, v8, v113, v133 op_sel_hi:[0,1,0]
	v_fma_mix_f32 v133, v9, v113, v133 op_sel:[0,1,0] op_sel_hi:[0,1,0]
	v_add_f32_dpp v12, v12, v12 row_ror:2 row_mask:0xf bank_mask:0xf bound_ctrl:1
	v_pk_fma_f32 v[48:49], v[150:151], v[70:71], v[6:7] op_sel_hi:[1,0,1]
	v_pk_fma_f32 v[50:51], v[152:153], v[70:71], v[8:9] op_sel_hi:[1,0,1]
	v_add_f32_dpp v12, v12, v12 row_ror:4 row_mask:0xf bank_mask:0xf bound_ctrl:1
	v_add_f32_dpp v62, v63, v62 quad_perm:[2,3,0,1] row_mask:0xf bank_mask:0xf bound_ctrl:1
	v_add_f32_dpp v63, v65, v64 quad_perm:[2,3,0,1] row_mask:0xf bank_mask:0xf bound_ctrl:1
	v_add_f32_dpp v12, v12, v12 row_ror:8 row_mask:0xf bank_mask:0xf bound_ctrl:1
	v_pk_fma_f32 v[6:7], v[146:147], v[12:13], v[48:49] op_sel_hi:[1,0,1] neg_lo:[1,0,0] neg_hi:[1,0,0]
	v_pk_fma_f32 v[8:9], v[148:149], v[12:13], v[50:51] op_sel_hi:[1,0,1] neg_lo:[1,0,0] neg_hi:[1,0,0]
	ds_read_b128 v[204:207], v10 offset:64768
	ds_read_b128 v[200:203], v10 offset:64512
	ds_read_b128 v[212:215], v10 offset:65280
	ds_read_b128 v[208:211], v10 offset:65024
	v_fma_mix_f32 v12, v6, v158, v180 op_sel_hi:[0,1,0]
	v_fma_mix_f32 v12, v7, v158, v12 op_sel:[0,1,0] op_sel_hi:[0,1,0]
	v_fma_mix_f32 v12, v8, v159, v12 op_sel_hi:[0,1,0]
	v_fma_mix_f32 v12, v9, v159, v12 op_sel:[0,1,0] op_sel_hi:[0,1,0]
	v_fma_mix_f32 v134, v6, v144, v180 op_sel_hi:[0,1,0]
	v_fma_mix_f32 v134, v7, v144, v134 op_sel:[0,1,0] op_sel_hi:[0,1,0]
	v_add_f32_dpp v12, v12, v12 row_ror:1 row_mask:0xf bank_mask:0xf bound_ctrl:1
	v_fma_mix_f32 v134, v8, v145, v134 op_sel_hi:[0,1,0]
	v_fma_mix_f32 v134, v9, v145, v134 op_sel:[0,1,0] op_sel_hi:[0,1,0]
	v_add_f32_dpp v12, v12, v12 row_ror:2 row_mask:0xf bank_mask:0xf bound_ctrl:1
	v_pk_fma_f32 v[48:49], v[166:167], v[70:71], v[6:7] op_sel:[0,1,0]
	v_pk_fma_f32 v[50:51], v[168:169], v[70:71], v[8:9] op_sel:[0,1,0]
	v_add_f32_dpp v12, v12, v12 row_ror:4 row_mask:0xf bank_mask:0xf bound_ctrl:1
	v_cndmask_b32_e64 v65, v63, v62, s[40:41]
	v_cndmask_b32_e64 v62, v62, v63, s[40:41]
	v_add_f32_dpp v12, v12, v12 row_ror:8 row_mask:0xf bank_mask:0xf bound_ctrl:1
	v_pk_fma_f32 v[6:7], v[162:163], v[12:13], v[48:49] op_sel_hi:[1,0,1] neg_lo:[1,0,0] neg_hi:[1,0,0]
	v_pk_fma_f32 v[8:9], v[164:165], v[12:13], v[50:51] op_sel_hi:[1,0,1] neg_lo:[1,0,0] neg_hi:[1,0,0]
	s_waitcnt lgkmcnt(0)
	s_nop 0
	v_fma_mix_f32 v12, v6, v188, v180 op_sel_hi:[0,1,0]
	v_fma_mix_f32 v12, v7, v188, v12 op_sel:[0,1,0] op_sel_hi:[0,1,0]
	v_fma_mix_f32 v12, v8, v189, v12 op_sel_hi:[0,1,0]
	v_fma_mix_f32 v12, v9, v189, v12 op_sel:[0,1,0] op_sel_hi:[0,1,0]
	v_fma_mix_f32 v135, v6, v160, v180 op_sel_hi:[0,1,0]
	v_fma_mix_f32 v135, v7, v160, v135 op_sel:[0,1,0] op_sel_hi:[0,1,0]
	v_add_f32_dpp v12, v12, v12 row_ror:1 row_mask:0xf bank_mask:0xf bound_ctrl:1
	v_fma_mix_f32 v135, v8, v161, v135 op_sel_hi:[0,1,0]
	v_fma_mix_f32 v135, v9, v161, v135 op_sel:[0,1,0] op_sel_hi:[0,1,0]
	v_add_f32_dpp v12, v12, v12 row_ror:2 row_mask:0xf bank_mask:0xf bound_ctrl:1
	v_pk_fma_f32 v[48:49], v[196:197], v[72:73], v[6:7] op_sel_hi:[1,0,1]
	v_pk_fma_f32 v[50:51], v[198:199], v[72:73], v[8:9] op_sel_hi:[1,0,1]
	v_add_f32_dpp v12, v12, v12 row_ror:4 row_mask:0xf bank_mask:0xf bound_ctrl:1
	v_add_f32_dpp v62, v62, v65 quad_perm:[1,0,3,2] row_mask:0xf bank_mask:0xf bound_ctrl:1
	v_cvt_pk_bf16_f32 v62, v62, v62
	v_add_f32_dpp v12, v12, v12 row_ror:8 row_mask:0xf bank_mask:0xf bound_ctrl:1
	v_pk_fma_f32 v[6:7], v[192:193], v[12:13], v[48:49] op_sel_hi:[1,0,1] neg_lo:[1,0,0] neg_hi:[1,0,0]
	v_pk_fma_f32 v[8:9], v[194:195], v[12:13], v[50:51] op_sel_hi:[1,0,1] neg_lo:[1,0,0] neg_hi:[1,0,0]
	s_waitcnt lgkmcnt(0)
	s_barrier
	v_xor_b32_e32 v10, 0x10000, v10
	v_xor_b32_e32 v11, 0x1000, v11
	ds_read_b128 v[66:69], v11 offset:0
	ds_read_b128 v[20:23], v10 offset:256
	ds_read_b128 v[28:31], v10 offset:768
	ds_read_b128 v[24:27], v10 offset:512
	ds_read_b128 v[36:39], v10 offset:1280
	ds_read_b128 v[44:47], v10 offset:1792
	ds_read_b128 v[40:43], v10 offset:1536
	ds_read_b128 v[88:91], v10 offset:2304
	ds_read_b128 v[96:99], v10 offset:2816
	ds_read_b128 v[92:95], v10 offset:2560
	v_fma_mix_f32 v12, v6, v204, v180 op_sel_hi:[0,1,0]
	v_fma_mix_f32 v12, v7, v204, v12 op_sel:[0,1,0] op_sel_hi:[0,1,0]
	v_fma_mix_f32 v12, v8, v205, v12 op_sel_hi:[0,1,0]
	v_fma_mix_f32 v12, v9, v205, v12 op_sel:[0,1,0] op_sel_hi:[0,1,0]
	v_fma_mix_f32 v136, v6, v190, v180 op_sel_hi:[0,1,0]
	v_fma_mix_f32 v136, v7, v190, v136 op_sel:[0,1,0] op_sel_hi:[0,1,0]
	v_add_f32_dpp v12, v12, v12 row_ror:1 row_mask:0xf bank_mask:0xf bound_ctrl:1
	v_fma_mix_f32 v136, v8, v191, v136 op_sel_hi:[0,1,0]
	v_fma_mix_f32 v136, v9, v191, v136 op_sel:[0,1,0] op_sel_hi:[0,1,0]
	v_add_f32_dpp v12, v12, v12 row_ror:2 row_mask:0xf bank_mask:0xf bound_ctrl:1
	v_pk_fma_f32 v[48:49], v[212:213], v[72:73], v[6:7] op_sel:[0,1,0]
	v_pk_fma_f32 v[50:51], v[214:215], v[72:73], v[8:9] op_sel:[0,1,0]
	v_add_f32_dpp v12, v12, v12 row_ror:4 row_mask:0xf bank_mask:0xf bound_ctrl:1
	global_store_short v[2:3], v62, off
	v_lshl_add_u64 v[2:3], v[2:3], 0, s[84:85]
	v_add_f32_dpp v12, v12, v12 row_ror:8 row_mask:0xf bank_mask:0xf bound_ctrl:1
	v_pk_fma_f32 v[6:7], v[208:209], v[12:13], v[48:49] op_sel_hi:[1,0,1] neg_lo:[1,0,0] neg_hi:[1,0,0]
	v_pk_fma_f32 v[8:9], v[210:211], v[12:13], v[50:51] op_sel_hi:[1,0,1] neg_lo:[1,0,0] neg_hi:[1,0,0]
	v_pk_mul_f32 v[6:7], v[6:7], v[200:201]
	v_pk_mul_f32 v[8:9], v[8:9], v[202:203]
	v_fma_mix_f32 v137, v6, v206, v180 op_sel_hi:[0,1,0]
	v_fma_mix_f32 v137, v7, v206, v137 op_sel:[0,1,0] op_sel_hi:[0,1,0]
	v_fma_mix_f32 v137, v8, v207, v137 op_sel_hi:[0,1,0]
	v_fma_mix_f32 v137, v9, v207, v137 op_sel:[0,1,0] op_sel_hi:[0,1,0]
	v_mov_b32_e64 v170, v2
	v_mov_b32_e64 v171, v3
	s_mov_b64 s[100:101], -1
	s_nop 0
	s_cmp_lg_u32 s28, 0x800000
	s_cbranch_scc1 .Lscan_cons_chunk
	v_add_f32_dpp v130, v130, v130 row_ror:8 row_mask:0xf bank_mask:0xc
	v_add_f32_dpp v130, v122, v122 row_ror:8 row_mask:0xf bank_mask:0x3
	v_add_f32_dpp v131, v131, v131 row_ror:8 row_mask:0xf bank_mask:0xc
	v_add_f32_dpp v131, v123, v123 row_ror:8 row_mask:0xf bank_mask:0x3
	v_add_f32_dpp v132, v132, v132 row_ror:8 row_mask:0xf bank_mask:0xc
	v_add_f32_dpp v132, v124, v124 row_ror:8 row_mask:0xf bank_mask:0x3
	v_add_f32_dpp v133, v133, v133 row_ror:8 row_mask:0xf bank_mask:0xc
	v_add_f32_dpp v133, v125, v125 row_ror:8 row_mask:0xf bank_mask:0x3
	v_add_f32_dpp v134, v134, v134 row_ror:8 row_mask:0xf bank_mask:0xc
	v_add_f32_dpp v134, v126, v126 row_ror:8 row_mask:0xf bank_mask:0x3
	v_add_f32_dpp v135, v135, v135 row_ror:8 row_mask:0xf bank_mask:0xc
	v_add_f32_dpp v135, v127, v127 row_ror:8 row_mask:0xf bank_mask:0x3
	v_add_f32_dpp v136, v136, v136 row_ror:8 row_mask:0xf bank_mask:0xc
	v_add_f32_dpp v136, v128, v128 row_ror:8 row_mask:0xf bank_mask:0x3
	v_add_f32_dpp v137, v137, v137 row_ror:8 row_mask:0xf bank_mask:0xc
	v_add_f32_dpp v137, v129, v129 row_ror:8 row_mask:0xf bank_mask:0x3
	v_add_f32_dpp v134, v134, v134 row_ror:4 row_mask:0xf bank_mask:0xa
	v_add_f32_dpp v134, v130, v130 row_ror:12 row_mask:0xf bank_mask:0x5
	v_add_f32_dpp v135, v135, v135 row_ror:4 row_mask:0xf bank_mask:0xa
	v_add_f32_dpp v135, v131, v131 row_ror:12 row_mask:0xf bank_mask:0x5
	v_add_f32_dpp v136, v136, v136 row_ror:4 row_mask:0xf bank_mask:0xa
	v_add_f32_dpp v136, v132, v132 row_ror:12 row_mask:0xf bank_mask:0x5
	v_add_f32_dpp v137, v137, v137 row_ror:4 row_mask:0xf bank_mask:0xa
	v_add_f32_dpp v137, v133, v133 row_ror:12 row_mask:0xf bank_mask:0x5
	v_cndmask_b32_e64 v62, v136, v134, s[38:39]
	v_cndmask_b32_e64 v63, v134, v136, s[38:39]
	v_cndmask_b32_e64 v64, v137, v135, s[38:39]
	v_cndmask_b32_e64 v65, v135, v137, s[38:39]
	v_add_f32_dpp v62, v63, v62 quad_perm:[2,3,0,1] row_mask:0xf bank_mask:0xf bound_ctrl:1
	s_nop 0
	v_add_f32_dpp v63, v65, v64 quad_perm:[2,3,0,1] row_mask:0xf bank_mask:0xf bound_ctrl:1
	v_cndmask_b32_e64 v65, v63, v62, s[40:41]
	v_cndmask_b32_e64 v62, v62, v63, s[40:41]
	s_nop 1
	v_add_f32_dpp v62, v62, v65 quad_perm:[1,0,3,2] row_mask:0xf bank_mask:0xf bound_ctrl:1
	v_cvt_pk_bf16_f32 v62, v62, v62
	global_store_short v[2:3], v62, off
	s_branch .LBB0_53

.Lprod_loop:
	s_nop 0
	s_cmp_eq_u32 s6, 0x7f
	s_cbranch_scc1 .Lprod_bar
	s_nop 0
	v_xor_b32_e32 v119, 0x10000, v119
	v_xor_b32_e32 v123, 0x1000, v123
	s_waitcnt vmcnt(0)
	s_nop 0
	v_cvt_f32_f16_e64 v124, v24
	v_cvt_f32_f16_sdwa v125, v24 dst_sel:DWORD dst_unused:UNUSED_PAD src0_sel:WORD_1
	v_cvt_f32_f16_e64 v126, v25
	v_cvt_f32_f16_sdwa v127, v25 dst_sel:DWORD dst_unused:UNUSED_PAD src0_sel:WORD_1
	v_cvt_f32_f16_e64 v128, v36
	v_cvt_f32_f16_sdwa v129, v36 dst_sel:DWORD dst_unused:UNUSED_PAD src0_sel:WORD_1
	v_cvt_f32_f16_e64 v130, v37
	v_cvt_f32_f16_sdwa v131, v37 dst_sel:DWORD dst_unused:UNUSED_PAD src0_sel:WORD_1
	v_cvt_f32_f16_e64 v132, v48
	v_cvt_f32_f16_sdwa v133, v48 dst_sel:DWORD dst_unused:UNUSED_PAD src0_sel:WORD_1
	v_cvt_f32_f16_e64 v134, v49
	v_cvt_f32_f16_sdwa v135, v49 dst_sel:DWORD dst_unused:UNUSED_PAD src0_sel:WORD_1
	v_cvt_f32_f16_e64 v136, v60
	v_cvt_f32_f16_sdwa v137, v60 dst_sel:DWORD dst_unused:UNUSED_PAD src0_sel:WORD_1
	v_cvt_f32_f16_e64 v138, v61
	v_cvt_f32_f16_sdwa v139, v61 dst_sel:DWORD dst_unused:UNUSED_PAD src0_sel:WORD_1
	v_pk_add_f32 v[128:129], v[128:129], v[124:125]
	v_pk_add_f32 v[130:131], v[130:131], v[126:127]
	v_pk_add_f32 v[132:133], v[132:133], v[128:129]
	v_pk_add_f32 v[134:135], v[134:135], v[130:131]
	v_pk_add_f32 v[136:137], v[136:137], v[132:133]
	v_pk_add_f32 v[138:139], v[138:139], v[134:135]
	v_exp_f32_e64 v140, -v124
	v_exp_f32_e64 v141, -v125
	v_exp_f32_e64 v142, -v126
	v_exp_f32_e64 v143, -v127
	v_exp_f32_e64 v144, -v128
	v_exp_f32_e64 v145, -v129
	v_exp_f32_e64 v146, -v130
	v_exp_f32_e64 v147, -v131
	v_exp_f32_e64 v148, -v132
	v_exp_f32_e64 v149, -v133
	v_exp_f32_e64 v150, -v134
	v_exp_f32_e64 v151, -v135
	v_exp_f32_e64 v152, -v136
	v_exp_f32_e64 v153, -v137
	v_exp_f32_e64 v154, -v138
	v_exp_f32_e64 v155, -v139
	v_exp_f32_e64 v156, v124
	v_exp_f32_e64 v157, v125
	v_exp_f32_e64 v158, v126
	v_exp_f32_e64 v159, v127
	v_exp_f32_e64 v160, v128
	v_exp_f32_e64 v161, v129
	v_exp_f32_e64 v162, v130
	v_exp_f32_e64 v163, v131
	v_exp_f32_e64 v164, v132
	v_exp_f32_e64 v165, v133
	v_exp_f32_e64 v166, v134
	v_exp_f32_e64 v167, v135
	v_exp_f32_e64 v168, v136
	v_exp_f32_e64 v169, v137
	v_exp_f32_e64 v170, v138
	v_exp_f32_e64 v171, v139
	v_cvt_f32_f16_e64 v68, v22
	v_cvt_f32_f16_sdwa v69, v22 dst_sel:DWORD dst_unused:UNUSED_PAD src0_sel:WORD_1
	v_cvt_f32_f16_e64 v70, v23
	v_cvt_f32_f16_sdwa v71, v23 dst_sel:DWORD dst_unused:UNUSED_PAD src0_sel:WORD_1
	v_lshlrev_b32_e64 v72, 16, v20
	v_and_b32_e32 v73, 0xffff0000, v20
	v_lshlrev_b32_e64 v74, 16, v21
	v_and_b32_e32 v75, 0xffff0000, v21
	v_lshlrev_b32_e64 v76, 16, v18
	v_and_b32_e32 v77, 0xffff0000, v18
	v_lshlrev_b32_e64 v78, 16, v19
	v_and_b32_e32 v79, 0xffff0000, v19
	v_lshlrev_b32_e64 v80, 16, v16
	v_and_b32_e32 v81, 0xffff0000, v16
	v_lshlrev_b32_e64 v82, 16, v17
	v_and_b32_e32 v83, 0xffff0000, v17
	v_pk_mul_f32 v[84:85], v[72:73], v[68:69]
	v_pk_mul_f32 v[86:87], v[74:75], v[70:71]
	v_pk_add_f32 v[88:89], v[68:69], -1.0 op_sel_hi:[1,0]
	v_pk_add_f32 v[90:91], v[70:71], -1.0 op_sel_hi:[1,0]
	v_pk_fma_f32 v[88:89], v[106:107], v[88:89], 1.0 op_sel_hi:[1,1,0]
	v_pk_fma_f32 v[90:91], v[108:109], v[90:91], 1.0 op_sel_hi:[1,1,0]
	v_pk_mul_f32 v[84:85], v[84:85], v[156:157]
	v_pk_mul_f32 v[86:87], v[86:87], v[158:159]
	v_pk_mul_f32 v[88:89], v[88:89], v[76:77]
	v_pk_mul_f32 v[90:91], v[90:91], v[78:79]
	ds_write_b128 v119, v[84:87] offset:512
	v_pk_mul_f32 v[88:89], v[88:89], v[156:157]
	v_pk_mul_f32 v[90:91], v[90:91], v[158:159]
	v_pk_mul_f32 v[80:81], v[80:81], v[140:141]
	v_pk_mul_f32 v[82:83], v[82:83], v[142:143]
	ds_write_b128 v119, v[88:91] offset:768
	v_lshlrev_b32_e64 v96, 16, v26
	v_cvt_pk_f16_f32 v92, v72, v73
	v_cvt_pk_f16_f32 v93, v74, v75
	v_cvt_pk_f16_f32 v94, v80, v81
	v_cvt_pk_f16_f32 v95, v82, v83
	ds_write_b128 v119, v[92:95] offset:256
	v_cvt_f32_f16_e64 v68, v34
	v_cvt_f32_f16_sdwa v69, v34 dst_sel:DWORD dst_unused:UNUSED_PAD src0_sel:WORD_1
	v_cvt_f32_f16_e64 v70, v35
	v_cvt_f32_f16_sdwa v71, v35 dst_sel:DWORD dst_unused:UNUSED_PAD src0_sel:WORD_1
	v_lshlrev_b32_e64 v72, 16, v32
	v_and_b32_e32 v73, 0xffff0000, v32
	v_lshlrev_b32_e64 v74, 16, v33
	v_and_b32_e32 v75, 0xffff0000, v33
	v_lshlrev_b32_e64 v76, 16, v30
	v_and_b32_e32 v77, 0xffff0000, v30
	v_lshlrev_b32_e64 v78, 16, v31
	v_and_b32_e32 v79, 0xffff0000, v31
	v_lshlrev_b32_e64 v80, 16, v28
	v_and_b32_e32 v81, 0xffff0000, v28
	v_lshlrev_b32_e64 v82, 16, v29
	v_and_b32_e32 v83, 0xffff0000, v29
	v_pk_mul_f32 v[84:85], v[72:73], v[68:69]
	v_pk_mul_f32 v[86:87], v[74:75], v[70:71]
	v_pk_add_f32 v[88:89], v[68:69], -1.0 op_sel_hi:[1,0]
	v_pk_add_f32 v[90:91], v[70:71], -1.0 op_sel_hi:[1,0]
	v_pk_fma_f32 v[88:89], v[106:107], v[88:89], 1.0 op_sel_hi:[1,1,0]
	v_pk_fma_f32 v[90:91], v[108:109], v[90:91], 1.0 op_sel_hi:[1,1,0]
	v_pk_mul_f32 v[84:85], v[84:85], v[160:161]
	v_pk_mul_f32 v[86:87], v[86:87], v[162:163]
	v_pk_mul_f32 v[88:89], v[88:89], v[76:77]
	v_pk_mul_f32 v[90:91], v[90:91], v[78:79]
	ds_write_b128 v119, v[84:87] offset:1536
	v_pk_mul_f32 v[88:89], v[88:89], v[160:161]
	v_pk_mul_f32 v[90:91], v[90:91], v[162:163]
	v_pk_mul_f32 v[72:73], v[72:73], v[140:141]
	v_pk_mul_f32 v[74:75], v[74:75], v[142:143]
	v_pk_mul_f32 v[80:81], v[80:81], v[144:145]
	v_pk_mul_f32 v[82:83], v[82:83], v[146:147]
	ds_write_b128 v119, v[88:91] offset:1792
	v_lshlrev_b32_e64 v97, 16, v38
	v_cvt_pk_f16_f32 v92, v72, v73
	v_cvt_pk_f16_f32 v93, v74, v75
	v_cvt_pk_f16_f32 v94, v80, v81
	v_cvt_pk_f16_f32 v95, v82, v83
	ds_write_b128 v119, v[92:95] offset:1280
	v_cvt_f32_f16_e64 v68, v46
	v_cvt_f32_f16_sdwa v69, v46 dst_sel:DWORD dst_unused:UNUSED_PAD src0_sel:WORD_1
	v_cvt_f32_f16_e64 v70, v47
	v_cvt_f32_f16_sdwa v71, v47 dst_sel:DWORD dst_unused:UNUSED_PAD src0_sel:WORD_1
	v_lshlrev_b32_e64 v72, 16, v44
	v_and_b32_e32 v73, 0xffff0000, v44
	v_lshlrev_b32_e64 v74, 16, v45
	v_and_b32_e32 v75, 0xffff0000, v45
	v_lshlrev_b32_e64 v76, 16, v42
	v_and_b32_e32 v77, 0xffff0000, v42
	v_lshlrev_b32_e64 v78, 16, v43
	v_and_b32_e32 v79, 0xffff0000, v43
	v_lshlrev_b32_e64 v80, 16, v40
	v_and_b32_e32 v81, 0xffff0000, v40
	v_lshlrev_b32_e64 v82, 16, v41
	v_and_b32_e32 v83, 0xffff0000, v41
	v_pk_mul_f32 v[84:85], v[72:73], v[68:69]
	v_pk_mul_f32 v[86:87], v[74:75], v[70:71]
	v_pk_add_f32 v[88:89], v[68:69], -1.0 op_sel_hi:[1,0]
	v_pk_add_f32 v[90:91], v[70:71], -1.0 op_sel_hi:[1,0]
	v_pk_fma_f32 v[88:89], v[106:107], v[88:89], 1.0 op_sel_hi:[1,1,0]
	v_pk_fma_f32 v[90:91], v[108:109], v[90:91], 1.0 op_sel_hi:[1,1,0]
	v_pk_mul_f32 v[84:85], v[84:85], v[164:165]
	v_pk_mul_f32 v[86:87], v[86:87], v[166:167]
	v_pk_mul_f32 v[88:89], v[88:89], v[76:77]
	v_pk_mul_f32 v[90:91], v[90:91], v[78:79]
	ds_write_b128 v119, v[84:87] offset:2560
	v_pk_mul_f32 v[88:89], v[88:89], v[164:165]
	v_pk_mul_f32 v[90:91], v[90:91], v[166:167]
	v_pk_mul_f32 v[72:73], v[72:73], v[144:145]
	v_pk_mul_f32 v[74:75], v[74:75], v[146:147]
	v_pk_mul_f32 v[80:81], v[80:81], v[148:149]
	v_pk_mul_f32 v[82:83], v[82:83], v[150:151]
	ds_write_b128 v119, v[88:91] offset:2816
	v_lshlrev_b32_e64 v98, 16, v50
	v_cvt_pk_f16_f32 v92, v72, v73
	v_cvt_pk_f16_f32 v93, v74, v75
	v_cvt_pk_f16_f32 v94, v80, v81
	v_cvt_pk_f16_f32 v95, v82, v83
	ds_write_b128 v119, v[92:95] offset:2304
	v_cvt_f32_f16_e64 v68, v58
	v_cvt_f32_f16_sdwa v69, v58 dst_sel:DWORD dst_unused:UNUSED_PAD src0_sel:WORD_1
	v_cvt_f32_f16_e64 v70, v59
	v_cvt_f32_f16_sdwa v71, v59 dst_sel:DWORD dst_unused:UNUSED_PAD src0_sel:WORD_1
	v_lshlrev_b32_e64 v72, 16, v56
	v_and_b32_e32 v73, 0xffff0000, v56
	v_lshlrev_b32_e64 v74, 16, v57
	v_and_b32_e32 v75, 0xffff0000, v57
	v_lshlrev_b32_e64 v76, 16, v54
	v_and_b32_e32 v77, 0xffff0000, v54
	v_lshlrev_b32_e64 v78, 16, v55
	v_and_b32_e32 v79, 0xffff0000, v55
	v_lshlrev_b32_e64 v80, 16, v52
	v_and_b32_e32 v81, 0xffff0000, v52
	v_lshlrev_b32_e64 v82, 16, v53
	v_and_b32_e32 v83, 0xffff0000, v53
	v_pk_mul_f32 v[84:85], v[72:73], v[68:69]
	v_pk_mul_f32 v[86:87], v[74:75], v[70:71]
	v_pk_add_f32 v[88:89], v[68:69], -1.0 op_sel_hi:[1,0]
	v_pk_add_f32 v[90:91], v[70:71], -1.0 op_sel_hi:[1,0]
	v_pk_fma_f32 v[88:89], v[106:107], v[88:89], 1.0 op_sel_hi:[1,1,0]
	v_pk_fma_f32 v[90:91], v[108:109], v[90:91], 1.0 op_sel_hi:[1,1,0]
	v_pk_mul_f32 v[84:85], v[84:85], v[168:169]
	v_pk_mul_f32 v[86:87], v[86:87], v[170:171]
	v_pk_mul_f32 v[88:89], v[88:89], v[76:77]
	v_pk_mul_f32 v[90:91], v[90:91], v[78:79]
	ds_write_b128 v119, v[84:87] offset:3584
	v_pk_mul_f32 v[88:89], v[88:89], v[168:169]
	v_pk_mul_f32 v[90:91], v[90:91], v[170:171]
	v_pk_mul_f32 v[72:73], v[72:73], v[148:149]
	v_pk_mul_f32 v[74:75], v[74:75], v[150:151]
	ds_write_b128 v119, v[88:91] offset:3840
	v_lshlrev_b32_e64 v99, 16, v62
	v_cvt_pk_f16_f32 v92, v72, v73
	v_cvt_pk_f16_f32 v93, v74, v75
	v_cvt_pk_f16_f32 v94, v80, v81
	v_cvt_pk_f16_f32 v95, v82, v83
	ds_write_b128 v119, v[92:95] offset:3328
	ds_write_b128 v119, v[152:155] offset:3072
	ds_write_b128 v123, v[96:99]
	s_cmp_ge_u32 s6, 0x7e
	s_cbranch_scc1 .Lprod_bar
	s_nop 0
	global_load_dwordx2 v[16:17], v110, s[44:45]
	global_load_dwordx2 v[18:19], v110, s[46:47]
	global_load_dwordx2 v[20:21], v110, s[8:9]
	global_load_dwordx2 v[22:23], v110, s[34:35]
	global_load_dwordx2 v[24:25], v110, s[28:29]
	global_load_ushort v26, v114, s[14:15]
	global_load_dwordx2 v[28:29], v111, s[44:45]
	global_load_dwordx2 v[30:31], v111, s[46:47]
	global_load_dwordx2 v[32:33], v111, s[8:9]
	global_load_dwordx2 v[34:35], v111, s[34:35]
	global_load_dwordx2 v[36:37], v111, s[28:29]
	global_load_ushort v38, v115, s[14:15]
	global_load_dwordx2 v[40:41], v112, s[44:45]
	global_load_dwordx2 v[42:43], v112, s[46:47]
	global_load_dwordx2 v[44:45], v112, s[8:9]
	global_load_dwordx2 v[46:47], v112, s[34:35]
	global_load_dwordx2 v[48:49], v112, s[28:29]
	global_load_ushort v50, v116, s[14:15]
	global_load_dwordx2 v[52:53], v113, s[44:45]
	global_load_dwordx2 v[54:55], v113, s[46:47]
	global_load_dwordx2 v[56:57], v113, s[8:9]
	global_load_dwordx2 v[58:59], v113, s[34:35]
	global_load_dwordx2 v[60:61], v113, s[28:29]
	global_load_ushort v62, v117, s[14:15]
	v_add_u32_e64 v110, s12, v110
	v_add_u32_e64 v114, s12, v114
	v_add_u32_e64 v111, s12, v111
	v_add_u32_e64 v115, s12, v115
	v_add_u32_e64 v112, s12, v112
	v_add_u32_e64 v116, s12, v116
	v_add_u32_e64 v113, s12, v113
	v_add_u32_e64 v117, s12, v117
.Lprod_bar:
	s_waitcnt lgkmcnt(0)
	s_barrier
	s_add_i32 s6, s6, 1
	s_nop 0
	s_cmp_lt_u32 s6, 0x80
	s_cbranch_scc1 .Lprod_loop
	s_branch .LBB0_52
